# attention steady loops: compiler lgkmcnt(0) drains replaced by minimal counted lgkmcnt waits (LDS fragment reads stay in flight across MFMAs)
# speedup vs baseline: 1.0037x; 1.0005x over previous
.Lst0_single:
	s_lshl_b32 s46, s41, 14
	s_add_i32 s46, s58, s46
	s_mov_b32 m0, s46
	s_nop 0
	global_load_lds_dwordx4 v198, s[98:99]
	s_add_i32 m0, s46, 0x400
	s_nop 0
	global_load_lds_dwordx4 v194, s[98:99]
	s_add_i32 s48, s20, 0xffffc000
	s_and_b32 s48, s48, 0x8000
	s_add_i32 s48, s58, s48
	s_add_i32 m0, s48, 0xc000
	s_nop 0
	global_load_lds_dwordx4 v196, s[100:101]
	s_add_i32 m0, s48, 0xc400
	s_nop 0
	global_load_lds_dwordx4 v192, s[100:101]
	s_add_i32 s46, s41, 1
	s_cmp_lg_u32 s41, 2
	s_cselect_b32 s41, s46, 0
	s_lshl_b32 s46, s41, 14
	s_add_i32 s49, s46, 0
	s_add_i32 s46, s20, 0xffff4000
	v_add_u32_e32 v100, s49, v205
	ds_read_b128 v[96:99], v100
	ds_read_b128 v[100:103], v100 offset:8192
	s_waitcnt lgkmcnt(1)
	v_mfma_f32_32x32x16_bf16 v[112:127], v[96:99], v[160:163], 0
	v_xad_u32 v104, v205, 32, s49
	ds_read_b128 v[128:131], v104
	ds_read_b128 v[132:135], v104 offset:8192
	v_xad_u32 v96, v205, 64, s49
	ds_read_b128 v[136:139], v96
	s_and_b32 s46, s46, 0x8000
	s_add_i32 s48, s46, 0
	v_exp_f32_e32 v140, v48
	v_exp_f32_e32 v141, v49
	v_exp_f32_e32 v142, v50
	v_exp_f32_e32 v143, v51
	ds_read_b128 v[48:51], v96 offset:8192
	s_waitcnt lgkmcnt(4)
	v_mfma_f32_32x32x16_bf16 v[96:111], v[100:103], v[160:163], 0
	v_exp_f32_e32 v144, v52
	v_exp_f32_e32 v145, v53
	v_exp_f32_e32 v146, v54
	v_exp_f32_e32 v147, v55
	s_waitcnt lgkmcnt(3)
	v_mfma_f32_32x32x16_bf16 v[112:127], v[128:131], v[164:167], v[112:127]
	v_add_u32_e32 v152, s49, v213
	ds_read_b128 v[52:55], v152
	v_exp_f32_e32 v148, v56
	v_exp_f32_e32 v149, v57
	v_exp_f32_e32 v150, v58
	v_exp_f32_e32 v151, v59
	s_waitcnt lgkmcnt(3)
	v_mfma_f32_32x32x16_bf16 v[96:111], v[132:135], v[164:167], v[96:111]
	ds_read_b128 v[56:59], v152 offset:8192
	v_exp_f32_e32 v128, v60
	v_exp_f32_e32 v129, v61
	v_exp_f32_e32 v130, v62
	v_exp_f32_e32 v131, v63
	s_waitcnt lgkmcnt(3)
	v_mfma_f32_32x32x16_bf16 v[112:127], v[136:139], v[168:171], v[112:127]
	v_add_u32_e32 v156, s48, v206
	ds_read_b128 v[60:63], v156 offset:49152
	v_exp_f32_e32 v132, v32
	v_exp_f32_e32 v133, v33
	v_exp_f32_e32 v134, v34
	v_exp_f32_e32 v135, v35
	s_waitcnt lgkmcnt(3)
	v_mfma_f32_32x32x16_bf16 v[96:111], v[48:51], v[168:171], v[96:111]
	ds_read_b128 v[32:35], v156 offset:53248
	v_exp_f32_e32 v136, v36
	v_exp_f32_e32 v137, v37
	v_exp_f32_e32 v138, v38
	v_exp_f32_e32 v139, v39
	s_waitcnt lgkmcnt(3)
	v_mfma_f32_32x32x16_bf16 v[112:127], v[52:55], v[172:175], v[112:127]
	ds_read_b128 v[36:39], v156 offset:57344
	v_exp_f32_e32 v152, v40
	v_exp_f32_e32 v153, v41
	v_exp_f32_e32 v154, v42
	v_exp_f32_e32 v155, v43
	s_waitcnt lgkmcnt(3)
	v_mfma_f32_32x32x16_bf16 v[96:111], v[56:59], v[172:175], v[96:111]
	ds_read_b128 v[40:43], v156 offset:61440
	v_exp_f32_e32 v156, v44
	v_exp_f32_e32 v157, v45
	v_exp_f32_e32 v158, v46
	v_exp_f32_e32 v159, v47
	v_cvt_pk_bf16_f32 v44, v140, v141
	v_cvt_pk_bf16_f32 v45, v142, v143
	v_cvt_pk_bf16_f32 v46, v144, v145
	v_cvt_pk_bf16_f32 v47, v146, v147
	s_nop 1
	s_waitcnt lgkmcnt(3)
	v_mfma_f32_32x32x16_bf16 v[80:95], v[60:63], v[44:47], v[80:95]
	v_xad_u32 v178, v206, 32, s48
	ds_read_b128 v[48:51], v178 offset:49152
	v_cvt_pk_bf16_f32 v52, v148, v149
	v_cvt_pk_bf16_f32 v53, v150, v151
	v_cvt_pk_bf16_f32 v54, v128, v129
	v_cvt_pk_bf16_f32 v55, v130, v131
	s_waitcnt lgkmcnt(3)
	v_mfma_f32_32x32x16_bf16 v[64:79], v[32:35], v[44:47], v[64:79]
	ds_read_b128 v[56:59], v178 offset:53248
	v_pk_add_f32 v[62:63], v[146:147], v[142:143]
	v_pk_add_f32 v[60:61], v[144:145], v[140:141]
	s_waitcnt lgkmcnt(3)
	v_mfma_f32_32x32x16_bf16 v[16:31], v[36:39], v[44:47], v[16:31]
	ds_read_b128 v[32:35], v178 offset:57344
	v_add_f32_e64 v62, v150, v62
	v_add_f32_e64 v63, v151, v63
	v_add_f32_e64 v60, v148, v60
	v_add_f32_e64 v61, v149, v61
	v_pk_add_f32 v[62:63], v[130:131], v[62:63]
	v_pk_add_f32 v[60:61], v[128:129], v[60:61]
	s_waitcnt lgkmcnt(3)
	v_mfma_f32_32x32x16_bf16 v[0:15], v[40:43], v[44:47], v[0:15]
	ds_read_b128 v[36:39], v178 offset:61440
	s_waitcnt lgkmcnt(3)
	v_mfma_f32_32x32x16_bf16 v[80:95], v[48:51], v[52:55], v[80:95]
	v_xad_u32 v140, v206, 64, s48
	ds_read_b128 v[40:43], v140 offset:49152
	v_cvt_pk_bf16_f32 v44, v132, v133
	v_cvt_pk_bf16_f32 v45, v134, v135
	v_cvt_pk_bf16_f32 v46, v136, v137
	v_cvt_pk_bf16_f32 v47, v138, v139
	s_waitcnt lgkmcnt(3)
	v_mfma_f32_32x32x16_bf16 v[64:79], v[56:59], v[52:55], v[64:79]
	ds_read_b128 v[48:51], v140 offset:53248
	v_add_f32_e64 v62, v134, v62
	v_add_f32_e64 v63, v135, v63
	v_add_f32_e64 v60, v132, v60
	v_add_f32_e64 v61, v133, v61
	v_pk_add_f32 v[62:63], v[138:139], v[62:63]
	v_pk_add_f32 v[60:61], v[136:137], v[60:61]
	s_waitcnt lgkmcnt(3)
	v_mfma_f32_32x32x16_bf16 v[16:31], v[32:35], v[52:55], v[16:31]
	ds_read_b128 v[56:59], v140 offset:57344
	v_add_f32_e64 v62, v154, v62
	v_add_f32_e64 v63, v155, v63
	v_add_f32_e64 v60, v152, v60
	v_add_f32_e64 v61, v153, v61
	v_pk_add_f32 v[130:131], v[158:159], v[62:63]
	v_pk_add_f32 v[128:129], v[156:157], v[60:61]
	s_waitcnt lgkmcnt(3)
	v_mfma_f32_32x32x16_bf16 v[0:15], v[36:39], v[52:55], v[0:15]
	ds_read_b128 v[32:35], v140 offset:61440
	s_waitcnt lgkmcnt(3)
	v_mfma_f32_32x32x16_bf16 v[80:95], v[40:43], v[44:47], v[80:95]
	v_add_u32_e32 v60, s48, v209
	ds_read_b128 v[36:39], v60 offset:49152
	v_cvt_pk_bf16_f32 v52, v152, v153
	v_cvt_pk_bf16_f32 v53, v154, v155
	v_cvt_pk_bf16_f32 v54, v156, v157
	v_cvt_pk_bf16_f32 v55, v158, v159
	s_waitcnt lgkmcnt(3)
	v_mfma_f32_32x32x16_bf16 v[64:79], v[48:51], v[44:47], v[64:79]
	ds_read_b128 v[40:43], v60 offset:53248
	s_waitcnt lgkmcnt(3)
	v_mfma_f32_32x32x16_bf16 v[16:31], v[56:59], v[44:47], v[16:31]
	ds_read_b128 v[48:51], v60 offset:57344
	s_waitcnt lgkmcnt(3)
	v_mfma_f32_32x32x16_bf16 v[0:15], v[32:35], v[44:47], v[0:15]
	ds_read_b128 v[56:59], v60 offset:61440
	s_waitcnt lgkmcnt(3)
	v_mfma_f32_32x32x16_bf16 v[80:95], v[36:39], v[52:55], v[80:95]
	s_waitcnt lgkmcnt(2)
	v_mfma_f32_32x32x16_bf16 v[64:79], v[40:43], v[52:55], v[64:79]
	s_waitcnt lgkmcnt(1)
	v_mfma_f32_32x32x16_bf16 v[16:31], v[48:51], v[52:55], v[16:31]
	s_waitcnt lgkmcnt(0)
	v_mfma_f32_32x32x16_bf16 v[0:15], v[56:59], v[52:55], v[0:15]
	s_waitcnt vmcnt(4) lgkmcnt(0)
	s_barrier
	s_add_u32 s68, s98, 0x18000
	s_addc_u32 s69, s99, 0
	s_add_i32 s49, s49, s57
	s_mov_b32 m0, s49
	s_nop 0
	global_load_lds_dwordx4 v198, s[68:69]
	s_add_i32 m0, s49, 0x400
	s_nop 0
	global_load_lds_dwordx4 v194, s[68:69]
	s_add_u32 s44, s100, 0x80
	s_addc_u32 s45, s101, 0
	s_and_b32 s49, s20, 0xc000
	s_add_i32 s49, s58, s49
	s_add_i32 m0, s49, 0xc000
	s_nop 0
	global_load_lds_dwordx4 v196, s[44:45]
	s_add_i32 m0, s49, 0xc400
	s_nop 0
	global_load_lds_dwordx4 v192, s[44:45]
	s_add_i32 s48, s48, 0xc000
	s_add_i32 s44, s41, 1
	s_cmp_lg_u32 s41, 2
	s_cselect_b32 s41, s44, 0
	s_lshl_b32 s44, s41, 14
	s_add_i32 s44, s44, 0
	v_exp_f32_e32 v144, v112
	v_add_u32_e32 v36, s44, v205
	ds_read_b128 v[32:35], v36
	ds_read_b128 v[36:39], v36 offset:8192
	s_waitcnt lgkmcnt(1)
	v_mfma_f32_32x32x16_bf16 v[48:63], v[32:35], v[160:163], 0
	v_xad_u32 v40, v205, 32, s44
	ds_read_b128 v[132:135], v40
	ds_read_b128 v[136:139], v40 offset:8192
	v_xad_u32 v32, v205, 64, s44
	ds_read_b128 v[140:143], v32
	v_exp_f32_e32 v145, v113
	v_exp_f32_e32 v146, v114
	v_exp_f32_e32 v147, v115
	ds_read_b128 v[112:115], v32 offset:8192
	s_waitcnt lgkmcnt(4)
	v_mfma_f32_32x32x16_bf16 v[32:47], v[36:39], v[160:163], 0
	v_exp_f32_e32 v148, v116
	v_exp_f32_e32 v149, v117
	v_exp_f32_e32 v150, v118
	v_exp_f32_e32 v151, v119
	s_waitcnt lgkmcnt(3)
	v_mfma_f32_32x32x16_bf16 v[48:63], v[132:135], v[164:167], v[48:63]
	v_add_u32_e32 v156, s44, v213
	ds_read_b128 v[116:119], v156
	v_exp_f32_e32 v152, v120
	v_exp_f32_e32 v153, v121
	v_exp_f32_e32 v154, v122
	v_exp_f32_e32 v155, v123
	s_waitcnt lgkmcnt(3)
	v_mfma_f32_32x32x16_bf16 v[32:47], v[136:139], v[164:167], v[32:47]
	ds_read_b128 v[120:123], v156 offset:8192
	v_exp_f32_e32 v156, v124
	v_exp_f32_e32 v157, v125
	v_exp_f32_e32 v158, v126
	v_exp_f32_e32 v159, v127
	s_waitcnt lgkmcnt(3)
	v_mfma_f32_32x32x16_bf16 v[48:63], v[140:143], v[168:171], v[48:63]
	v_add_u32_e32 v132, s48, v206
	ds_read_b128 v[124:127], v132 offset:16384
	v_exp_f32_e32 v136, v96
	v_exp_f32_e32 v137, v97
	v_exp_f32_e32 v138, v98
	v_exp_f32_e32 v139, v99
	s_waitcnt lgkmcnt(3)
	v_mfma_f32_32x32x16_bf16 v[32:47], v[112:115], v[168:171], v[32:47]
	ds_read_b128 v[96:99], v132 offset:20480
	v_exp_f32_e32 v140, v100
	v_exp_f32_e32 v141, v101
	v_exp_f32_e32 v142, v102
	v_exp_f32_e32 v143, v103
	s_waitcnt lgkmcnt(3)
	v_mfma_f32_32x32x16_bf16 v[48:63], v[116:119], v[172:175], v[48:63]
	ds_read_b128 v[100:103], v132 offset:24576
	v_exp_f32_e32 v178, v104
	v_exp_f32_e32 v179, v105
	v_exp_f32_e32 v180, v106
	v_exp_f32_e32 v181, v107
	s_waitcnt lgkmcnt(3)
	v_mfma_f32_32x32x16_bf16 v[32:47], v[120:123], v[172:175], v[32:47]
	ds_read_b128 v[104:107], v132 offset:28672
	v_exp_f32_e32 v182, v108
	v_exp_f32_e32 v183, v109
	v_exp_f32_e32 v184, v110
	v_exp_f32_e32 v185, v111
	v_cvt_pk_bf16_f32 v108, v144, v145
	v_cvt_pk_bf16_f32 v109, v146, v147
	v_cvt_pk_bf16_f32 v110, v148, v149
	v_cvt_pk_bf16_f32 v111, v150, v151
	s_nop 1
	s_waitcnt lgkmcnt(3)
	v_mfma_f32_32x32x16_bf16 v[80:95], v[124:127], v[108:111], v[80:95]
	v_xad_u32 v186, v206, 32, s48
	ds_read_b128 v[112:115], v186 offset:16384
	v_cvt_pk_bf16_f32 v116, v152, v153
	v_cvt_pk_bf16_f32 v117, v154, v155
	v_cvt_pk_bf16_f32 v118, v156, v157
	v_cvt_pk_bf16_f32 v119, v158, v159
	s_waitcnt lgkmcnt(3)
	v_mfma_f32_32x32x16_bf16 v[64:79], v[96:99], v[108:111], v[64:79]
	ds_read_b128 v[120:123], v186 offset:20480
	v_pk_add_f32 v[126:127], v[150:151], v[146:147]
	v_pk_add_f32 v[124:125], v[148:149], v[144:145]
	s_waitcnt lgkmcnt(3)
	v_mfma_f32_32x32x16_bf16 v[16:31], v[100:103], v[108:111], v[16:31]
	ds_read_b128 v[132:135], v186 offset:24576
	v_add_f32_e64 v98, v154, v126
	v_add_f32_e64 v99, v155, v127
	v_add_f32_e64 v96, v152, v124
	v_add_f32_e64 v97, v153, v125
	v_pk_add_f32 v[98:99], v[158:159], v[98:99]
	v_pk_add_f32 v[96:97], v[156:157], v[96:97]
	s_waitcnt lgkmcnt(3)
	v_mfma_f32_32x32x16_bf16 v[0:15], v[104:107], v[108:111], v[0:15]
	ds_read_b128 v[100:103], v186 offset:28672
	s_waitcnt lgkmcnt(3)
	v_mfma_f32_32x32x16_bf16 v[80:95], v[112:115], v[116:119], v[80:95]
	v_xad_u32 v124, v206, 64, s48
	ds_read_b128 v[104:107], v124 offset:16384
	v_cvt_pk_bf16_f32 v108, v136, v137
	v_cvt_pk_bf16_f32 v109, v138, v139
	v_cvt_pk_bf16_f32 v110, v140, v141
	v_cvt_pk_bf16_f32 v111, v142, v143
	s_waitcnt lgkmcnt(3)
	v_mfma_f32_32x32x16_bf16 v[64:79], v[120:123], v[116:119], v[64:79]
	ds_read_b128 v[112:115], v124 offset:20480
	v_add_f32_e64 v98, v138, v98
	v_add_f32_e64 v99, v139, v99
	v_add_f32_e64 v96, v136, v96
	v_add_f32_e64 v97, v137, v97
	v_pk_add_f32 v[98:99], v[142:143], v[98:99]
	v_pk_add_f32 v[96:97], v[140:141], v[96:97]
	s_waitcnt lgkmcnt(3)
	v_mfma_f32_32x32x16_bf16 v[16:31], v[132:135], v[116:119], v[16:31]
	ds_read_b128 v[120:123], v124 offset:24576
	v_add_f32_e64 v98, v180, v98
	v_add_f32_e64 v99, v181, v99
	v_add_f32_e64 v96, v178, v96
	v_add_f32_e64 v97, v179, v97
	v_pk_add_f32 v[98:99], v[184:185], v[98:99]
	v_pk_add_f32 v[96:97], v[182:183], v[96:97]
	s_waitcnt lgkmcnt(3)
	v_mfma_f32_32x32x16_bf16 v[0:15], v[100:103], v[116:119], v[0:15]
	ds_read_b128 v[124:127], v124 offset:28672
	s_waitcnt lgkmcnt(3)
	v_mfma_f32_32x32x16_bf16 v[80:95], v[104:107], v[108:111], v[80:95]
	v_add_u32_e32 v132, s48, v209
	ds_read_b128 v[100:103], v132 offset:16384
	v_cvt_pk_bf16_f32 v116, v178, v179
	v_cvt_pk_bf16_f32 v117, v180, v181
	v_cvt_pk_bf16_f32 v118, v182, v183
	v_cvt_pk_bf16_f32 v119, v184, v185
	s_waitcnt lgkmcnt(3)
	v_mfma_f32_32x32x16_bf16 v[64:79], v[112:115], v[108:111], v[64:79]
	ds_read_b128 v[104:107], v132 offset:20480
	s_waitcnt lgkmcnt(3)
	v_mfma_f32_32x32x16_bf16 v[16:31], v[120:123], v[108:111], v[16:31]
	ds_read_b128 v[112:115], v132 offset:24576
	s_waitcnt lgkmcnt(3)
	v_mfma_f32_32x32x16_bf16 v[0:15], v[124:127], v[108:111], v[0:15]
	ds_read_b128 v[120:123], v132 offset:28672
	s_waitcnt lgkmcnt(3)
	v_mfma_f32_32x32x16_bf16 v[80:95], v[100:103], v[116:119], v[80:95]
	s_waitcnt lgkmcnt(2)
	v_mfma_f32_32x32x16_bf16 v[64:79], v[104:107], v[116:119], v[64:79]
	s_waitcnt lgkmcnt(1)
	v_mfma_f32_32x32x16_bf16 v[16:31], v[112:115], v[116:119], v[16:31]
	s_waitcnt lgkmcnt(0)
	v_mfma_f32_32x32x16_bf16 v[0:15], v[120:123], v[116:119], v[0:15]
	s_waitcnt vmcnt(4) lgkmcnt(0)
	v_add_f32_e32 v100, v128, v129
	v_add_f32_e32 v101, v130, v131
	v_add_f32_e32 v100, v100, v101
	v_add_f32_e32 v96, v96, v97
	v_add_f32_e32 v97, v98, v99
	s_barrier
	v_add_f32_e32 v100, v177, v100
	v_add_f32_e32 v96, v96, v97
	v_add_f32_e32 v177, v100, v96
	s_add_i32 s21, s21, 2
	s_addk_i32 s15, 0x80
	s_add_i32 s20, s20, 0x8000
	s_add_u32 s98, s98, 0x30000
	s_addc_u32 s99, s99, 0
	s_add_u32 s100, s100, 0x100
	s_addc_u32 s101, s101, 0
	s_cmp_lt_u32 s21, 60
	s_cbranch_scc1 .Lst0_loop
	s_branch .Lst0_exit
.Lst0_u3:
	s_lshl_b32 s46, s41, 14
	s_add_i32 s46, s58, s46
	s_mov_b32 m0, s46
	s_nop 0
	global_load_lds_dwordx4 v198, s[98:99]
	s_add_i32 m0, s46, 0x400
	s_nop 0
	global_load_lds_dwordx4 v194, s[98:99]
	s_add_i32 s48, s20, 0xffffc000
	s_and_b32 s48, s48, 0x8000
	s_add_i32 s48, s58, s48
	s_add_i32 m0, s48, 0xc000
	s_nop 0
	global_load_lds_dwordx4 v196, s[100:101]
	s_add_i32 m0, s48, 0xc400
	s_nop 0
	global_load_lds_dwordx4 v192, s[100:101]
	s_add_i32 s46, s41, 1
	s_cmp_lg_u32 s41, 2
	s_cselect_b32 s41, s46, 0
	s_lshl_b32 s46, s41, 14
	s_add_i32 s49, s46, 0
	s_add_i32 s46, s20, 0xffff4000
	ds_read_b128 v[96:99], v205 offset:16384
	ds_read_b128 v[100:103], v205 offset:24576
	s_waitcnt lgkmcnt(1)
	v_mfma_f32_32x32x16_bf16 v[112:127], v[96:99], v[160:163], 0
	ds_read_b128 v[128:131], v211 offset:16384
	ds_read_b128 v[132:135], v211 offset:24576
	ds_read_b128 v[136:139], v212 offset:16384
	s_and_b32 s46, s46, 0x8000
	s_add_i32 s48, s46, 0
	v_exp_f32_e32 v140, v48
	v_exp_f32_e32 v141, v49
	v_exp_f32_e32 v142, v50
	v_exp_f32_e32 v143, v51
	ds_read_b128 v[48:51], v212 offset:24576
	s_waitcnt lgkmcnt(4)
	v_mfma_f32_32x32x16_bf16 v[96:111], v[100:103], v[160:163], 0
	v_exp_f32_e32 v144, v52
	v_exp_f32_e32 v145, v53
	v_exp_f32_e32 v146, v54
	v_exp_f32_e32 v147, v55
	s_waitcnt lgkmcnt(3)
	v_mfma_f32_32x32x16_bf16 v[112:127], v[128:131], v[164:167], v[112:127]
	ds_read_b128 v[52:55], v213 offset:16384
	v_exp_f32_e32 v148, v56
	v_exp_f32_e32 v149, v57
	v_exp_f32_e32 v150, v58
	v_exp_f32_e32 v151, v59
	s_waitcnt lgkmcnt(3)
	v_mfma_f32_32x32x16_bf16 v[96:111], v[132:135], v[164:167], v[96:111]
	ds_read_b128 v[56:59], v213 offset:24576
	v_exp_f32_e32 v128, v60
	v_exp_f32_e32 v129, v61
	v_exp_f32_e32 v130, v62
	v_exp_f32_e32 v131, v63
	s_waitcnt lgkmcnt(3)
	v_mfma_f32_32x32x16_bf16 v[112:127], v[136:139], v[168:171], v[112:127]
	v_add_u32_e32 v156, s48, v206
	ds_read_b128 v[60:63], v156 offset:49152
	v_exp_f32_e32 v132, v32
	v_exp_f32_e32 v133, v33
	v_exp_f32_e32 v134, v34
	v_exp_f32_e32 v135, v35
	s_waitcnt lgkmcnt(3)
	v_mfma_f32_32x32x16_bf16 v[96:111], v[48:51], v[168:171], v[96:111]
	ds_read_b128 v[32:35], v156 offset:53248
	v_exp_f32_e32 v136, v36
	v_exp_f32_e32 v137, v37
	v_exp_f32_e32 v138, v38
	v_exp_f32_e32 v139, v39
	s_waitcnt lgkmcnt(3)
	v_mfma_f32_32x32x16_bf16 v[112:127], v[52:55], v[172:175], v[112:127]
	ds_read_b128 v[36:39], v156 offset:57344
	v_exp_f32_e32 v152, v40
	v_exp_f32_e32 v153, v41
	v_exp_f32_e32 v154, v42
	v_exp_f32_e32 v155, v43
	s_waitcnt lgkmcnt(3)
	v_mfma_f32_32x32x16_bf16 v[96:111], v[56:59], v[172:175], v[96:111]
	ds_read_b128 v[40:43], v156 offset:61440
	v_exp_f32_e32 v156, v44
	v_exp_f32_e32 v157, v45
	v_exp_f32_e32 v158, v46
	v_exp_f32_e32 v159, v47
	v_cvt_pk_bf16_f32 v44, v140, v141
	v_cvt_pk_bf16_f32 v45, v142, v143
	v_cvt_pk_bf16_f32 v46, v144, v145
	v_cvt_pk_bf16_f32 v47, v146, v147
	s_nop 1
	s_waitcnt lgkmcnt(3)
	v_mfma_f32_32x32x16_bf16 v[80:95], v[60:63], v[44:47], v[80:95]
	v_xad_u32 v178, v206, 32, s48
	ds_read_b128 v[48:51], v178 offset:49152
	v_cvt_pk_bf16_f32 v52, v148, v149
	v_cvt_pk_bf16_f32 v53, v150, v151
	v_cvt_pk_bf16_f32 v54, v128, v129
	v_cvt_pk_bf16_f32 v55, v130, v131
	s_waitcnt lgkmcnt(3)
	v_mfma_f32_32x32x16_bf16 v[64:79], v[32:35], v[44:47], v[64:79]
	ds_read_b128 v[56:59], v178 offset:53248
	v_pk_add_f32 v[62:63], v[146:147], v[142:143]
	v_pk_add_f32 v[60:61], v[144:145], v[140:141]
	s_waitcnt lgkmcnt(3)
	v_mfma_f32_32x32x16_bf16 v[16:31], v[36:39], v[44:47], v[16:31]
	ds_read_b128 v[32:35], v178 offset:57344
	v_add_f32_e64 v62, v150, v62
	v_add_f32_e64 v63, v151, v63
	v_add_f32_e64 v60, v148, v60
	v_add_f32_e64 v61, v149, v61
	v_pk_add_f32 v[62:63], v[130:131], v[62:63]
	v_pk_add_f32 v[60:61], v[128:129], v[60:61]
	s_waitcnt lgkmcnt(3)
	v_mfma_f32_32x32x16_bf16 v[0:15], v[40:43], v[44:47], v[0:15]
	ds_read_b128 v[36:39], v178 offset:61440
	s_waitcnt lgkmcnt(3)
	v_mfma_f32_32x32x16_bf16 v[80:95], v[48:51], v[52:55], v[80:95]
	v_xad_u32 v140, v206, 64, s48
	ds_read_b128 v[40:43], v140 offset:49152
	v_cvt_pk_bf16_f32 v44, v132, v133
	v_cvt_pk_bf16_f32 v45, v134, v135
	v_cvt_pk_bf16_f32 v46, v136, v137
	v_cvt_pk_bf16_f32 v47, v138, v139
	s_waitcnt lgkmcnt(3)
	v_mfma_f32_32x32x16_bf16 v[64:79], v[56:59], v[52:55], v[64:79]
	ds_read_b128 v[48:51], v140 offset:53248
	v_add_f32_e64 v62, v134, v62
	v_add_f32_e64 v63, v135, v63
	v_add_f32_e64 v60, v132, v60
	v_add_f32_e64 v61, v133, v61
	v_pk_add_f32 v[62:63], v[138:139], v[62:63]
	v_pk_add_f32 v[60:61], v[136:137], v[60:61]
	s_waitcnt lgkmcnt(3)
	v_mfma_f32_32x32x16_bf16 v[16:31], v[32:35], v[52:55], v[16:31]
	ds_read_b128 v[56:59], v140 offset:57344
	v_add_f32_e64 v62, v154, v62
	v_add_f32_e64 v63, v155, v63
	v_add_f32_e64 v60, v152, v60
	v_add_f32_e64 v61, v153, v61
	v_pk_add_f32 v[130:131], v[158:159], v[62:63]
	v_pk_add_f32 v[128:129], v[156:157], v[60:61]
	s_waitcnt lgkmcnt(3)
	v_mfma_f32_32x32x16_bf16 v[0:15], v[36:39], v[52:55], v[0:15]
	ds_read_b128 v[32:35], v140 offset:61440
	s_waitcnt lgkmcnt(3)
	v_mfma_f32_32x32x16_bf16 v[80:95], v[40:43], v[44:47], v[80:95]
	v_add_u32_e32 v60, s48, v209
	ds_read_b128 v[36:39], v60 offset:49152
	v_cvt_pk_bf16_f32 v52, v152, v153
	v_cvt_pk_bf16_f32 v53, v154, v155
	v_cvt_pk_bf16_f32 v54, v156, v157
	v_cvt_pk_bf16_f32 v55, v158, v159
	s_waitcnt lgkmcnt(3)
	v_mfma_f32_32x32x16_bf16 v[64:79], v[48:51], v[44:47], v[64:79]
	ds_read_b128 v[40:43], v60 offset:53248
	s_waitcnt lgkmcnt(3)
	v_mfma_f32_32x32x16_bf16 v[16:31], v[56:59], v[44:47], v[16:31]
	ds_read_b128 v[48:51], v60 offset:57344
	s_waitcnt lgkmcnt(3)
	v_mfma_f32_32x32x16_bf16 v[0:15], v[32:35], v[44:47], v[0:15]
	ds_read_b128 v[56:59], v60 offset:61440
	s_waitcnt lgkmcnt(3)
	v_mfma_f32_32x32x16_bf16 v[80:95], v[36:39], v[52:55], v[80:95]
	s_waitcnt lgkmcnt(2)
	v_mfma_f32_32x32x16_bf16 v[64:79], v[40:43], v[52:55], v[64:79]
	s_waitcnt lgkmcnt(1)
	v_mfma_f32_32x32x16_bf16 v[16:31], v[48:51], v[52:55], v[16:31]
	s_waitcnt lgkmcnt(0)
	v_mfma_f32_32x32x16_bf16 v[0:15], v[56:59], v[52:55], v[0:15]
	s_waitcnt vmcnt(4) lgkmcnt(0)
	s_barrier
	s_add_u32 s68, s98, 0x18000
	s_addc_u32 s69, s99, 0
	s_add_i32 s49, s49, s57
	s_mov_b32 m0, s49
	s_nop 0
	global_load_lds_dwordx4 v198, s[68:69]
	s_add_i32 m0, s49, 0x400
	s_nop 0
	global_load_lds_dwordx4 v194, s[68:69]
	s_add_u32 s44, s100, 0x80
	s_addc_u32 s45, s101, 0
	s_and_b32 s49, s20, 0xc000
	s_add_i32 s49, s58, s49
	s_add_i32 m0, s49, 0xc000
	s_nop 0
	global_load_lds_dwordx4 v196, s[44:45]
	s_add_i32 m0, s49, 0xc400
	s_nop 0
	global_load_lds_dwordx4 v192, s[44:45]
	s_add_i32 s48, s48, 0xc000
	s_add_i32 s44, s41, 1
	s_cmp_lg_u32 s41, 2
	s_cselect_b32 s41, s44, 0
	s_lshl_b32 s44, s41, 14
	s_add_i32 s44, s44, 0
	v_exp_f32_e32 v144, v112
	ds_read_b128 v[32:35], v205 offset:32768
	ds_read_b128 v[36:39], v205 offset:40960
	s_waitcnt lgkmcnt(1)
	v_mfma_f32_32x32x16_bf16 v[48:63], v[32:35], v[160:163], 0
	ds_read_b128 v[132:135], v211 offset:32768
	ds_read_b128 v[136:139], v211 offset:40960
	ds_read_b128 v[140:143], v212 offset:32768
	v_exp_f32_e32 v145, v113
	v_exp_f32_e32 v146, v114
	v_exp_f32_e32 v147, v115
	ds_read_b128 v[112:115], v212 offset:40960
	s_waitcnt lgkmcnt(4)
	v_mfma_f32_32x32x16_bf16 v[32:47], v[36:39], v[160:163], 0
	v_exp_f32_e32 v148, v116
	v_exp_f32_e32 v149, v117
	v_exp_f32_e32 v150, v118
	v_exp_f32_e32 v151, v119
	s_waitcnt lgkmcnt(3)
	v_mfma_f32_32x32x16_bf16 v[48:63], v[132:135], v[164:167], v[48:63]
	ds_read_b128 v[116:119], v213 offset:32768
	v_exp_f32_e32 v152, v120
	v_exp_f32_e32 v153, v121
	v_exp_f32_e32 v154, v122
	v_exp_f32_e32 v155, v123
	s_waitcnt lgkmcnt(3)
	v_mfma_f32_32x32x16_bf16 v[32:47], v[136:139], v[164:167], v[32:47]
	ds_read_b128 v[120:123], v213 offset:40960
	v_exp_f32_e32 v156, v124
	v_exp_f32_e32 v157, v125
	v_exp_f32_e32 v158, v126
	v_exp_f32_e32 v159, v127
	s_waitcnt lgkmcnt(3)
	v_mfma_f32_32x32x16_bf16 v[48:63], v[140:143], v[168:171], v[48:63]
	v_add_u32_e32 v132, s48, v206
	ds_read_b128 v[124:127], v132 offset:16384
	v_exp_f32_e32 v136, v96
	v_exp_f32_e32 v137, v97
	v_exp_f32_e32 v138, v98
	v_exp_f32_e32 v139, v99
	s_waitcnt lgkmcnt(3)
	v_mfma_f32_32x32x16_bf16 v[32:47], v[112:115], v[168:171], v[32:47]
	ds_read_b128 v[96:99], v132 offset:20480
	v_exp_f32_e32 v140, v100
	v_exp_f32_e32 v141, v101
	v_exp_f32_e32 v142, v102
	v_exp_f32_e32 v143, v103
	s_waitcnt lgkmcnt(3)
	v_mfma_f32_32x32x16_bf16 v[48:63], v[116:119], v[172:175], v[48:63]
	ds_read_b128 v[100:103], v132 offset:24576
	v_exp_f32_e32 v178, v104
	v_exp_f32_e32 v179, v105
	v_exp_f32_e32 v180, v106
	v_exp_f32_e32 v181, v107
	s_waitcnt lgkmcnt(3)
	v_mfma_f32_32x32x16_bf16 v[32:47], v[120:123], v[172:175], v[32:47]
	ds_read_b128 v[104:107], v132 offset:28672
	v_exp_f32_e32 v182, v108
	v_exp_f32_e32 v183, v109
	v_exp_f32_e32 v184, v110
	v_exp_f32_e32 v185, v111
	v_cvt_pk_bf16_f32 v108, v144, v145
	v_cvt_pk_bf16_f32 v109, v146, v147
	v_cvt_pk_bf16_f32 v110, v148, v149
	v_cvt_pk_bf16_f32 v111, v150, v151
	s_nop 1
	s_waitcnt lgkmcnt(3)
	v_mfma_f32_32x32x16_bf16 v[80:95], v[124:127], v[108:111], v[80:95]
	v_xad_u32 v186, v206, 32, s48
	ds_read_b128 v[112:115], v186 offset:16384
	v_cvt_pk_bf16_f32 v116, v152, v153
	v_cvt_pk_bf16_f32 v117, v154, v155
	v_cvt_pk_bf16_f32 v118, v156, v157
	v_cvt_pk_bf16_f32 v119, v158, v159
	s_waitcnt lgkmcnt(3)
	v_mfma_f32_32x32x16_bf16 v[64:79], v[96:99], v[108:111], v[64:79]
	ds_read_b128 v[120:123], v186 offset:20480
	v_pk_add_f32 v[126:127], v[150:151], v[146:147]
	v_pk_add_f32 v[124:125], v[148:149], v[144:145]
	s_waitcnt lgkmcnt(3)
	v_mfma_f32_32x32x16_bf16 v[16:31], v[100:103], v[108:111], v[16:31]
	ds_read_b128 v[132:135], v186 offset:24576
	v_add_f32_e64 v98, v154, v126
	v_add_f32_e64 v99, v155, v127
	v_add_f32_e64 v96, v152, v124
	v_add_f32_e64 v97, v153, v125
	v_pk_add_f32 v[98:99], v[158:159], v[98:99]
	v_pk_add_f32 v[96:97], v[156:157], v[96:97]
	s_waitcnt lgkmcnt(3)
	v_mfma_f32_32x32x16_bf16 v[0:15], v[104:107], v[108:111], v[0:15]
	ds_read_b128 v[100:103], v186 offset:28672
	s_waitcnt lgkmcnt(3)
	v_mfma_f32_32x32x16_bf16 v[80:95], v[112:115], v[116:119], v[80:95]
	v_xad_u32 v124, v206, 64, s48
	ds_read_b128 v[104:107], v124 offset:16384
	v_cvt_pk_bf16_f32 v108, v136, v137
	v_cvt_pk_bf16_f32 v109, v138, v139
	v_cvt_pk_bf16_f32 v110, v140, v141
	v_cvt_pk_bf16_f32 v111, v142, v143
	s_waitcnt lgkmcnt(3)
	v_mfma_f32_32x32x16_bf16 v[64:79], v[120:123], v[116:119], v[64:79]
	ds_read_b128 v[112:115], v124 offset:20480
	v_add_f32_e64 v98, v138, v98
	v_add_f32_e64 v99, v139, v99
	v_add_f32_e64 v96, v136, v96
	v_add_f32_e64 v97, v137, v97
	v_pk_add_f32 v[98:99], v[142:143], v[98:99]
	v_pk_add_f32 v[96:97], v[140:141], v[96:97]
	s_waitcnt lgkmcnt(3)
	v_mfma_f32_32x32x16_bf16 v[16:31], v[132:135], v[116:119], v[16:31]
	ds_read_b128 v[120:123], v124 offset:24576
	v_add_f32_e64 v98, v180, v98
	v_add_f32_e64 v99, v181, v99
	v_add_f32_e64 v96, v178, v96
	v_add_f32_e64 v97, v179, v97
	v_pk_add_f32 v[98:99], v[184:185], v[98:99]
	v_pk_add_f32 v[96:97], v[182:183], v[96:97]
	s_waitcnt lgkmcnt(3)
	v_mfma_f32_32x32x16_bf16 v[0:15], v[100:103], v[116:119], v[0:15]
	ds_read_b128 v[124:127], v124 offset:28672
	s_waitcnt lgkmcnt(3)
	v_mfma_f32_32x32x16_bf16 v[80:95], v[104:107], v[108:111], v[80:95]
	v_add_u32_e32 v132, s48, v209
	ds_read_b128 v[100:103], v132 offset:16384
	v_cvt_pk_bf16_f32 v116, v178, v179
	v_cvt_pk_bf16_f32 v117, v180, v181
	v_cvt_pk_bf16_f32 v118, v182, v183
	v_cvt_pk_bf16_f32 v119, v184, v185
	s_waitcnt lgkmcnt(3)
	v_mfma_f32_32x32x16_bf16 v[64:79], v[112:115], v[108:111], v[64:79]
	ds_read_b128 v[104:107], v132 offset:20480
	s_waitcnt lgkmcnt(3)
	v_mfma_f32_32x32x16_bf16 v[16:31], v[120:123], v[108:111], v[16:31]
	ds_read_b128 v[112:115], v132 offset:24576
	s_waitcnt lgkmcnt(3)
	v_mfma_f32_32x32x16_bf16 v[0:15], v[124:127], v[108:111], v[0:15]
	ds_read_b128 v[120:123], v132 offset:28672
	s_waitcnt lgkmcnt(3)
	v_mfma_f32_32x32x16_bf16 v[80:95], v[100:103], v[116:119], v[80:95]
	s_waitcnt lgkmcnt(2)
	v_mfma_f32_32x32x16_bf16 v[64:79], v[104:107], v[116:119], v[64:79]
	s_waitcnt lgkmcnt(1)
	v_mfma_f32_32x32x16_bf16 v[16:31], v[112:115], v[116:119], v[16:31]
	s_waitcnt lgkmcnt(0)
	v_mfma_f32_32x32x16_bf16 v[0:15], v[120:123], v[116:119], v[0:15]
	s_waitcnt vmcnt(4) lgkmcnt(0)
	v_add_f32_e32 v100, v128, v129
	v_add_f32_e32 v101, v130, v131
	v_add_f32_e32 v100, v100, v101
	v_add_f32_e32 v96, v96, v97
	v_add_f32_e32 v97, v98, v99
	s_barrier
	v_add_f32_e32 v100, v177, v100
	v_add_f32_e32 v96, v96, v97
	v_add_f32_e32 v177, v100, v96
	s_add_i32 s21, s21, 2
	s_addk_i32 s15, 0x80
	s_add_i32 s20, s20, 0x8000
	s_add_u32 s98, s98, 0x30000
	s_addc_u32 s99, s99, 0
	s_add_u32 s100, s100, 0x100
	s_addc_u32 s101, s101, 0
	s_lshl_b32 s46, s41, 14
	s_add_i32 s46, s58, s46
	s_mov_b32 m0, s46
	s_nop 0
	global_load_lds_dwordx4 v198, s[98:99]
	s_add_i32 m0, s46, 0x400
	s_nop 0
	global_load_lds_dwordx4 v194, s[98:99]
	s_add_i32 s48, s20, 0xffffc000
	s_and_b32 s48, s48, 0x8000
	s_add_i32 s48, s58, s48
	s_add_i32 m0, s48, 0xc000
	s_nop 0
	global_load_lds_dwordx4 v196, s[100:101]
	s_add_i32 m0, s48, 0xc400
	s_nop 0
	global_load_lds_dwordx4 v192, s[100:101]
	s_add_i32 s46, s41, 1
	s_cmp_lg_u32 s41, 2
	s_cselect_b32 s41, s46, 0
	s_lshl_b32 s46, s41, 14
	s_add_i32 s49, s46, 0
	s_add_i32 s46, s20, 0xffff4000
	ds_read_b128 v[96:99], v205
	ds_read_b128 v[100:103], v205 offset:8192
	s_waitcnt lgkmcnt(1)
	v_mfma_f32_32x32x16_bf16 v[112:127], v[96:99], v[160:163], 0
	ds_read_b128 v[128:131], v211
	ds_read_b128 v[132:135], v211 offset:8192
	ds_read_b128 v[136:139], v212
	s_and_b32 s46, s46, 0x8000
	s_add_i32 s48, s46, 0
	v_exp_f32_e32 v140, v48
	v_exp_f32_e32 v141, v49
	v_exp_f32_e32 v142, v50
	v_exp_f32_e32 v143, v51
	ds_read_b128 v[48:51], v212 offset:8192
	s_waitcnt lgkmcnt(4)
	v_mfma_f32_32x32x16_bf16 v[96:111], v[100:103], v[160:163], 0
	v_exp_f32_e32 v144, v52
	v_exp_f32_e32 v145, v53
	v_exp_f32_e32 v146, v54
	v_exp_f32_e32 v147, v55
	s_waitcnt lgkmcnt(3)
	v_mfma_f32_32x32x16_bf16 v[112:127], v[128:131], v[164:167], v[112:127]
	ds_read_b128 v[52:55], v213
	v_exp_f32_e32 v148, v56
	v_exp_f32_e32 v149, v57
	v_exp_f32_e32 v150, v58
	v_exp_f32_e32 v151, v59
	s_waitcnt lgkmcnt(3)
	v_mfma_f32_32x32x16_bf16 v[96:111], v[132:135], v[164:167], v[96:111]
	ds_read_b128 v[56:59], v213 offset:8192
	v_exp_f32_e32 v128, v60
	v_exp_f32_e32 v129, v61
	v_exp_f32_e32 v130, v62
	v_exp_f32_e32 v131, v63
	s_waitcnt lgkmcnt(3)
	v_mfma_f32_32x32x16_bf16 v[112:127], v[136:139], v[168:171], v[112:127]
	v_add_u32_e32 v156, s48, v206
	ds_read_b128 v[60:63], v156 offset:49152
	v_exp_f32_e32 v132, v32
	v_exp_f32_e32 v133, v33
	v_exp_f32_e32 v134, v34
	v_exp_f32_e32 v135, v35
	s_waitcnt lgkmcnt(3)
	v_mfma_f32_32x32x16_bf16 v[96:111], v[48:51], v[168:171], v[96:111]
	ds_read_b128 v[32:35], v156 offset:53248
	v_exp_f32_e32 v136, v36
	v_exp_f32_e32 v137, v37
	v_exp_f32_e32 v138, v38
	v_exp_f32_e32 v139, v39
	s_waitcnt lgkmcnt(3)
	v_mfma_f32_32x32x16_bf16 v[112:127], v[52:55], v[172:175], v[112:127]
	ds_read_b128 v[36:39], v156 offset:57344
	v_exp_f32_e32 v152, v40
	v_exp_f32_e32 v153, v41
	v_exp_f32_e32 v154, v42
	v_exp_f32_e32 v155, v43
	s_waitcnt lgkmcnt(3)
	v_mfma_f32_32x32x16_bf16 v[96:111], v[56:59], v[172:175], v[96:111]
	ds_read_b128 v[40:43], v156 offset:61440
	v_exp_f32_e32 v156, v44
	v_exp_f32_e32 v157, v45
	v_exp_f32_e32 v158, v46
	v_exp_f32_e32 v159, v47
	v_cvt_pk_bf16_f32 v44, v140, v141
	v_cvt_pk_bf16_f32 v45, v142, v143
	v_cvt_pk_bf16_f32 v46, v144, v145
	v_cvt_pk_bf16_f32 v47, v146, v147
	s_nop 1
	s_waitcnt lgkmcnt(3)
	v_mfma_f32_32x32x16_bf16 v[80:95], v[60:63], v[44:47], v[80:95]
	v_xad_u32 v178, v206, 32, s48
	ds_read_b128 v[48:51], v178 offset:49152
	v_cvt_pk_bf16_f32 v52, v148, v149
	v_cvt_pk_bf16_f32 v53, v150, v151
	v_cvt_pk_bf16_f32 v54, v128, v129
	v_cvt_pk_bf16_f32 v55, v130, v131
	s_waitcnt lgkmcnt(3)
	v_mfma_f32_32x32x16_bf16 v[64:79], v[32:35], v[44:47], v[64:79]
	ds_read_b128 v[56:59], v178 offset:53248
	v_pk_add_f32 v[62:63], v[146:147], v[142:143]
	v_pk_add_f32 v[60:61], v[144:145], v[140:141]
	s_waitcnt lgkmcnt(3)
	v_mfma_f32_32x32x16_bf16 v[16:31], v[36:39], v[44:47], v[16:31]
	ds_read_b128 v[32:35], v178 offset:57344
	v_add_f32_e64 v62, v150, v62
	v_add_f32_e64 v63, v151, v63
	v_add_f32_e64 v60, v148, v60
	v_add_f32_e64 v61, v149, v61
	v_pk_add_f32 v[62:63], v[130:131], v[62:63]
	v_pk_add_f32 v[60:61], v[128:129], v[60:61]
	s_waitcnt lgkmcnt(3)
	v_mfma_f32_32x32x16_bf16 v[0:15], v[40:43], v[44:47], v[0:15]
	ds_read_b128 v[36:39], v178 offset:61440
	s_waitcnt lgkmcnt(3)
	v_mfma_f32_32x32x16_bf16 v[80:95], v[48:51], v[52:55], v[80:95]
	v_xad_u32 v140, v206, 64, s48
	ds_read_b128 v[40:43], v140 offset:49152
	v_cvt_pk_bf16_f32 v44, v132, v133
	v_cvt_pk_bf16_f32 v45, v134, v135
	v_cvt_pk_bf16_f32 v46, v136, v137
	v_cvt_pk_bf16_f32 v47, v138, v139
	s_waitcnt lgkmcnt(3)
	v_mfma_f32_32x32x16_bf16 v[64:79], v[56:59], v[52:55], v[64:79]
	ds_read_b128 v[48:51], v140 offset:53248
	v_add_f32_e64 v62, v134, v62
	v_add_f32_e64 v63, v135, v63
	v_add_f32_e64 v60, v132, v60
	v_add_f32_e64 v61, v133, v61
	v_pk_add_f32 v[62:63], v[138:139], v[62:63]
	v_pk_add_f32 v[60:61], v[136:137], v[60:61]
	s_waitcnt lgkmcnt(3)
	v_mfma_f32_32x32x16_bf16 v[16:31], v[32:35], v[52:55], v[16:31]
	ds_read_b128 v[56:59], v140 offset:57344
	v_add_f32_e64 v62, v154, v62
	v_add_f32_e64 v63, v155, v63
	v_add_f32_e64 v60, v152, v60
	v_add_f32_e64 v61, v153, v61
	v_pk_add_f32 v[130:131], v[158:159], v[62:63]
	v_pk_add_f32 v[128:129], v[156:157], v[60:61]
	s_waitcnt lgkmcnt(3)
	v_mfma_f32_32x32x16_bf16 v[0:15], v[36:39], v[52:55], v[0:15]
	ds_read_b128 v[32:35], v140 offset:61440
	s_waitcnt lgkmcnt(3)
	v_mfma_f32_32x32x16_bf16 v[80:95], v[40:43], v[44:47], v[80:95]
	v_add_u32_e32 v60, s48, v209
	ds_read_b128 v[36:39], v60 offset:49152
	v_cvt_pk_bf16_f32 v52, v152, v153
	v_cvt_pk_bf16_f32 v53, v154, v155
	v_cvt_pk_bf16_f32 v54, v156, v157
	v_cvt_pk_bf16_f32 v55, v158, v159
	s_waitcnt lgkmcnt(3)
	v_mfma_f32_32x32x16_bf16 v[64:79], v[48:51], v[44:47], v[64:79]
	ds_read_b128 v[40:43], v60 offset:53248
	s_waitcnt lgkmcnt(3)
	v_mfma_f32_32x32x16_bf16 v[16:31], v[56:59], v[44:47], v[16:31]
	ds_read_b128 v[48:51], v60 offset:57344
	s_waitcnt lgkmcnt(3)
	v_mfma_f32_32x32x16_bf16 v[0:15], v[32:35], v[44:47], v[0:15]
	ds_read_b128 v[56:59], v60 offset:61440
	s_waitcnt lgkmcnt(3)
	v_mfma_f32_32x32x16_bf16 v[80:95], v[36:39], v[52:55], v[80:95]
	s_waitcnt lgkmcnt(2)
	v_mfma_f32_32x32x16_bf16 v[64:79], v[40:43], v[52:55], v[64:79]
	s_waitcnt lgkmcnt(1)
	v_mfma_f32_32x32x16_bf16 v[16:31], v[48:51], v[52:55], v[16:31]
	s_waitcnt lgkmcnt(0)
	v_mfma_f32_32x32x16_bf16 v[0:15], v[56:59], v[52:55], v[0:15]
	s_waitcnt vmcnt(4) lgkmcnt(0)
	s_barrier
	s_add_u32 s68, s98, 0x18000
	s_addc_u32 s69, s99, 0
	s_add_i32 s49, s49, s57
	s_mov_b32 m0, s49
	s_nop 0
	global_load_lds_dwordx4 v198, s[68:69]
	s_add_i32 m0, s49, 0x400
	s_nop 0
	global_load_lds_dwordx4 v194, s[68:69]
	s_add_u32 s44, s100, 0x80
	s_addc_u32 s45, s101, 0
	s_and_b32 s49, s20, 0xc000
	s_add_i32 s49, s58, s49
	s_add_i32 m0, s49, 0xc000
	s_nop 0
	global_load_lds_dwordx4 v196, s[44:45]
	s_add_i32 m0, s49, 0xc400
	s_nop 0
	global_load_lds_dwordx4 v192, s[44:45]
	s_add_i32 s48, s48, 0xc000
	s_add_i32 s44, s41, 1
	s_cmp_lg_u32 s41, 2
	s_cselect_b32 s41, s44, 0
	s_lshl_b32 s44, s41, 14
	s_add_i32 s44, s44, 0
	v_exp_f32_e32 v144, v112
	ds_read_b128 v[32:35], v205 offset:16384
	ds_read_b128 v[36:39], v205 offset:24576
	s_waitcnt lgkmcnt(1)
	v_mfma_f32_32x32x16_bf16 v[48:63], v[32:35], v[160:163], 0
	ds_read_b128 v[132:135], v211 offset:16384
	ds_read_b128 v[136:139], v211 offset:24576
	ds_read_b128 v[140:143], v212 offset:16384
	v_exp_f32_e32 v145, v113
	v_exp_f32_e32 v146, v114
	v_exp_f32_e32 v147, v115
	ds_read_b128 v[112:115], v212 offset:24576
	s_waitcnt lgkmcnt(4)
	v_mfma_f32_32x32x16_bf16 v[32:47], v[36:39], v[160:163], 0
	v_exp_f32_e32 v148, v116
	v_exp_f32_e32 v149, v117
	v_exp_f32_e32 v150, v118
	v_exp_f32_e32 v151, v119
	s_waitcnt lgkmcnt(3)
	v_mfma_f32_32x32x16_bf16 v[48:63], v[132:135], v[164:167], v[48:63]
	ds_read_b128 v[116:119], v213 offset:16384
	v_exp_f32_e32 v152, v120
	v_exp_f32_e32 v153, v121
	v_exp_f32_e32 v154, v122
	v_exp_f32_e32 v155, v123
	s_waitcnt lgkmcnt(3)
	v_mfma_f32_32x32x16_bf16 v[32:47], v[136:139], v[164:167], v[32:47]
	ds_read_b128 v[120:123], v213 offset:24576
	v_exp_f32_e32 v156, v124
	v_exp_f32_e32 v157, v125
	v_exp_f32_e32 v158, v126
	v_exp_f32_e32 v159, v127
	s_waitcnt lgkmcnt(3)
	v_mfma_f32_32x32x16_bf16 v[48:63], v[140:143], v[168:171], v[48:63]
	v_add_u32_e32 v132, s48, v206
	ds_read_b128 v[124:127], v132 offset:16384
	v_exp_f32_e32 v136, v96
	v_exp_f32_e32 v137, v97
	v_exp_f32_e32 v138, v98
	v_exp_f32_e32 v139, v99
	s_waitcnt lgkmcnt(3)
	v_mfma_f32_32x32x16_bf16 v[32:47], v[112:115], v[168:171], v[32:47]
	ds_read_b128 v[96:99], v132 offset:20480
	v_exp_f32_e32 v140, v100
	v_exp_f32_e32 v141, v101
	v_exp_f32_e32 v142, v102
	v_exp_f32_e32 v143, v103
	s_waitcnt lgkmcnt(3)
	v_mfma_f32_32x32x16_bf16 v[48:63], v[116:119], v[172:175], v[48:63]
	ds_read_b128 v[100:103], v132 offset:24576
	v_exp_f32_e32 v178, v104
	v_exp_f32_e32 v179, v105
	v_exp_f32_e32 v180, v106
	v_exp_f32_e32 v181, v107
	s_waitcnt lgkmcnt(3)
	v_mfma_f32_32x32x16_bf16 v[32:47], v[120:123], v[172:175], v[32:47]
	ds_read_b128 v[104:107], v132 offset:28672
	v_exp_f32_e32 v182, v108
	v_exp_f32_e32 v183, v109
	v_exp_f32_e32 v184, v110
	v_exp_f32_e32 v185, v111
	v_cvt_pk_bf16_f32 v108, v144, v145
	v_cvt_pk_bf16_f32 v109, v146, v147
	v_cvt_pk_bf16_f32 v110, v148, v149
	v_cvt_pk_bf16_f32 v111, v150, v151
	s_nop 1
	s_waitcnt lgkmcnt(3)
	v_mfma_f32_32x32x16_bf16 v[80:95], v[124:127], v[108:111], v[80:95]
	v_xad_u32 v186, v206, 32, s48
	ds_read_b128 v[112:115], v186 offset:16384
	v_cvt_pk_bf16_f32 v116, v152, v153
	v_cvt_pk_bf16_f32 v117, v154, v155
	v_cvt_pk_bf16_f32 v118, v156, v157
	v_cvt_pk_bf16_f32 v119, v158, v159
	s_waitcnt lgkmcnt(3)
	v_mfma_f32_32x32x16_bf16 v[64:79], v[96:99], v[108:111], v[64:79]
	ds_read_b128 v[120:123], v186 offset:20480
	v_pk_add_f32 v[126:127], v[150:151], v[146:147]
	v_pk_add_f32 v[124:125], v[148:149], v[144:145]
	s_waitcnt lgkmcnt(3)
	v_mfma_f32_32x32x16_bf16 v[16:31], v[100:103], v[108:111], v[16:31]
	ds_read_b128 v[132:135], v186 offset:24576
	v_add_f32_e64 v98, v154, v126
	v_add_f32_e64 v99, v155, v127
	v_add_f32_e64 v96, v152, v124
	v_add_f32_e64 v97, v153, v125
	v_pk_add_f32 v[98:99], v[158:159], v[98:99]
	v_pk_add_f32 v[96:97], v[156:157], v[96:97]
	s_waitcnt lgkmcnt(3)
	v_mfma_f32_32x32x16_bf16 v[0:15], v[104:107], v[108:111], v[0:15]
	ds_read_b128 v[100:103], v186 offset:28672
	s_waitcnt lgkmcnt(3)
	v_mfma_f32_32x32x16_bf16 v[80:95], v[112:115], v[116:119], v[80:95]
	v_xad_u32 v124, v206, 64, s48
	ds_read_b128 v[104:107], v124 offset:16384
	v_cvt_pk_bf16_f32 v108, v136, v137
	v_cvt_pk_bf16_f32 v109, v138, v139
	v_cvt_pk_bf16_f32 v110, v140, v141
	v_cvt_pk_bf16_f32 v111, v142, v143
	s_waitcnt lgkmcnt(3)
	v_mfma_f32_32x32x16_bf16 v[64:79], v[120:123], v[116:119], v[64:79]
	ds_read_b128 v[112:115], v124 offset:20480
	v_add_f32_e64 v98, v138, v98
	v_add_f32_e64 v99, v139, v99
	v_add_f32_e64 v96, v136, v96
	v_add_f32_e64 v97, v137, v97
	v_pk_add_f32 v[98:99], v[142:143], v[98:99]
	v_pk_add_f32 v[96:97], v[140:141], v[96:97]
	s_waitcnt lgkmcnt(3)
	v_mfma_f32_32x32x16_bf16 v[16:31], v[132:135], v[116:119], v[16:31]
	ds_read_b128 v[120:123], v124 offset:24576
	v_add_f32_e64 v98, v180, v98
	v_add_f32_e64 v99, v181, v99
	v_add_f32_e64 v96, v178, v96
	v_add_f32_e64 v97, v179, v97
	v_pk_add_f32 v[98:99], v[184:185], v[98:99]
	v_pk_add_f32 v[96:97], v[182:183], v[96:97]
	s_waitcnt lgkmcnt(3)
	v_mfma_f32_32x32x16_bf16 v[0:15], v[100:103], v[116:119], v[0:15]
	ds_read_b128 v[124:127], v124 offset:28672
	s_waitcnt lgkmcnt(3)
	v_mfma_f32_32x32x16_bf16 v[80:95], v[104:107], v[108:111], v[80:95]
	v_add_u32_e32 v132, s48, v209
	ds_read_b128 v[100:103], v132 offset:16384
	v_cvt_pk_bf16_f32 v116, v178, v179
	v_cvt_pk_bf16_f32 v117, v180, v181
	v_cvt_pk_bf16_f32 v118, v182, v183
	v_cvt_pk_bf16_f32 v119, v184, v185
	s_waitcnt lgkmcnt(3)
	v_mfma_f32_32x32x16_bf16 v[64:79], v[112:115], v[108:111], v[64:79]
	ds_read_b128 v[104:107], v132 offset:20480
	s_waitcnt lgkmcnt(3)
	v_mfma_f32_32x32x16_bf16 v[16:31], v[120:123], v[108:111], v[16:31]
	ds_read_b128 v[112:115], v132 offset:24576
	s_waitcnt lgkmcnt(3)
	v_mfma_f32_32x32x16_bf16 v[0:15], v[124:127], v[108:111], v[0:15]
	ds_read_b128 v[120:123], v132 offset:28672
	s_waitcnt lgkmcnt(3)
	v_mfma_f32_32x32x16_bf16 v[80:95], v[100:103], v[116:119], v[80:95]
	s_waitcnt lgkmcnt(2)
	v_mfma_f32_32x32x16_bf16 v[64:79], v[104:107], v[116:119], v[64:79]
	s_waitcnt lgkmcnt(1)
	v_mfma_f32_32x32x16_bf16 v[16:31], v[112:115], v[116:119], v[16:31]
	s_waitcnt lgkmcnt(0)
	v_mfma_f32_32x32x16_bf16 v[0:15], v[120:123], v[116:119], v[0:15]
	s_waitcnt vmcnt(4) lgkmcnt(0)
	v_add_f32_e32 v100, v128, v129
	v_add_f32_e32 v101, v130, v131
	v_add_f32_e32 v100, v100, v101
	v_add_f32_e32 v96, v96, v97
	v_add_f32_e32 v97, v98, v99
	s_barrier
	v_add_f32_e32 v100, v177, v100
	v_add_f32_e32 v96, v96, v97
	v_add_f32_e32 v177, v100, v96
	s_add_i32 s21, s21, 2
	s_addk_i32 s15, 0x80
	s_add_i32 s20, s20, 0x8000
	s_add_u32 s98, s98, 0x30000
	s_addc_u32 s99, s99, 0
	s_add_u32 s100, s100, 0x100
	s_addc_u32 s101, s101, 0
	s_lshl_b32 s46, s41, 14
	s_add_i32 s46, s58, s46
	s_mov_b32 m0, s46
	s_nop 0
	global_load_lds_dwordx4 v198, s[98:99]
	s_add_i32 m0, s46, 0x400
	s_nop 0
	global_load_lds_dwordx4 v194, s[98:99]
	s_add_i32 s48, s20, 0xffffc000
	s_and_b32 s48, s48, 0x8000
	s_add_i32 s48, s58, s48
	s_add_i32 m0, s48, 0xc000
	s_nop 0
	global_load_lds_dwordx4 v196, s[100:101]
	s_add_i32 m0, s48, 0xc400
	s_nop 0
	global_load_lds_dwordx4 v192, s[100:101]
	s_add_i32 s46, s41, 1
	s_cmp_lg_u32 s41, 2
	s_cselect_b32 s41, s46, 0
	s_lshl_b32 s46, s41, 14
	s_add_i32 s49, s46, 0
	s_add_i32 s46, s20, 0xffff4000
	ds_read_b128 v[96:99], v205 offset:32768
	ds_read_b128 v[100:103], v205 offset:40960
	s_waitcnt lgkmcnt(1)
	v_mfma_f32_32x32x16_bf16 v[112:127], v[96:99], v[160:163], 0
	ds_read_b128 v[128:131], v211 offset:32768
	ds_read_b128 v[132:135], v211 offset:40960
	ds_read_b128 v[136:139], v212 offset:32768
	s_and_b32 s46, s46, 0x8000
	s_add_i32 s48, s46, 0
	v_exp_f32_e32 v140, v48
	v_exp_f32_e32 v141, v49
	v_exp_f32_e32 v142, v50
	v_exp_f32_e32 v143, v51
	ds_read_b128 v[48:51], v212 offset:40960
	s_waitcnt lgkmcnt(4)
	v_mfma_f32_32x32x16_bf16 v[96:111], v[100:103], v[160:163], 0
	v_exp_f32_e32 v144, v52
	v_exp_f32_e32 v145, v53
	v_exp_f32_e32 v146, v54
	v_exp_f32_e32 v147, v55
	s_waitcnt lgkmcnt(3)
	v_mfma_f32_32x32x16_bf16 v[112:127], v[128:131], v[164:167], v[112:127]
	ds_read_b128 v[52:55], v213 offset:32768
	v_exp_f32_e32 v148, v56
	v_exp_f32_e32 v149, v57
	v_exp_f32_e32 v150, v58
	v_exp_f32_e32 v151, v59
	s_waitcnt lgkmcnt(3)
	v_mfma_f32_32x32x16_bf16 v[96:111], v[132:135], v[164:167], v[96:111]
	ds_read_b128 v[56:59], v213 offset:40960
	v_exp_f32_e32 v128, v60
	v_exp_f32_e32 v129, v61
	v_exp_f32_e32 v130, v62
	v_exp_f32_e32 v131, v63
	s_waitcnt lgkmcnt(3)
	v_mfma_f32_32x32x16_bf16 v[112:127], v[136:139], v[168:171], v[112:127]
	v_add_u32_e32 v156, s48, v206
	ds_read_b128 v[60:63], v156 offset:49152
	v_exp_f32_e32 v132, v32
	v_exp_f32_e32 v133, v33
	v_exp_f32_e32 v134, v34
	v_exp_f32_e32 v135, v35
	s_waitcnt lgkmcnt(3)
	v_mfma_f32_32x32x16_bf16 v[96:111], v[48:51], v[168:171], v[96:111]
	ds_read_b128 v[32:35], v156 offset:53248
	v_exp_f32_e32 v136, v36
	v_exp_f32_e32 v137, v37
	v_exp_f32_e32 v138, v38
	v_exp_f32_e32 v139, v39
	s_waitcnt lgkmcnt(3)
	v_mfma_f32_32x32x16_bf16 v[112:127], v[52:55], v[172:175], v[112:127]
	ds_read_b128 v[36:39], v156 offset:57344
	v_exp_f32_e32 v152, v40
	v_exp_f32_e32 v153, v41
	v_exp_f32_e32 v154, v42
	v_exp_f32_e32 v155, v43
	s_waitcnt lgkmcnt(3)
	v_mfma_f32_32x32x16_bf16 v[96:111], v[56:59], v[172:175], v[96:111]
	ds_read_b128 v[40:43], v156 offset:61440
	v_exp_f32_e32 v156, v44
	v_exp_f32_e32 v157, v45
	v_exp_f32_e32 v158, v46
	v_exp_f32_e32 v159, v47
	v_cvt_pk_bf16_f32 v44, v140, v141
	v_cvt_pk_bf16_f32 v45, v142, v143
	v_cvt_pk_bf16_f32 v46, v144, v145
	v_cvt_pk_bf16_f32 v47, v146, v147
	s_nop 1
	s_waitcnt lgkmcnt(3)
	v_mfma_f32_32x32x16_bf16 v[80:95], v[60:63], v[44:47], v[80:95]
	v_xad_u32 v178, v206, 32, s48
	ds_read_b128 v[48:51], v178 offset:49152
	v_cvt_pk_bf16_f32 v52, v148, v149
	v_cvt_pk_bf16_f32 v53, v150, v151
	v_cvt_pk_bf16_f32 v54, v128, v129
	v_cvt_pk_bf16_f32 v55, v130, v131
	s_waitcnt lgkmcnt(3)
	v_mfma_f32_32x32x16_bf16 v[64:79], v[32:35], v[44:47], v[64:79]
	ds_read_b128 v[56:59], v178 offset:53248
	v_pk_add_f32 v[62:63], v[146:147], v[142:143]
	v_pk_add_f32 v[60:61], v[144:145], v[140:141]
	s_waitcnt lgkmcnt(3)
	v_mfma_f32_32x32x16_bf16 v[16:31], v[36:39], v[44:47], v[16:31]
	ds_read_b128 v[32:35], v178 offset:57344
	v_add_f32_e64 v62, v150, v62
	v_add_f32_e64 v63, v151, v63
	v_add_f32_e64 v60, v148, v60
	v_add_f32_e64 v61, v149, v61
	v_pk_add_f32 v[62:63], v[130:131], v[62:63]
	v_pk_add_f32 v[60:61], v[128:129], v[60:61]
	s_waitcnt lgkmcnt(3)
	v_mfma_f32_32x32x16_bf16 v[0:15], v[40:43], v[44:47], v[0:15]
	ds_read_b128 v[36:39], v178 offset:61440
	s_waitcnt lgkmcnt(3)
	v_mfma_f32_32x32x16_bf16 v[80:95], v[48:51], v[52:55], v[80:95]
	v_xad_u32 v140, v206, 64, s48
	ds_read_b128 v[40:43], v140 offset:49152
	v_cvt_pk_bf16_f32 v44, v132, v133
	v_cvt_pk_bf16_f32 v45, v134, v135
	v_cvt_pk_bf16_f32 v46, v136, v137
	v_cvt_pk_bf16_f32 v47, v138, v139
	s_waitcnt lgkmcnt(3)
	v_mfma_f32_32x32x16_bf16 v[64:79], v[56:59], v[52:55], v[64:79]
	ds_read_b128 v[48:51], v140 offset:53248
	v_add_f32_e64 v62, v134, v62
	v_add_f32_e64 v63, v135, v63
	v_add_f32_e64 v60, v132, v60
	v_add_f32_e64 v61, v133, v61
	v_pk_add_f32 v[62:63], v[138:139], v[62:63]
	v_pk_add_f32 v[60:61], v[136:137], v[60:61]
	s_waitcnt lgkmcnt(3)
	v_mfma_f32_32x32x16_bf16 v[16:31], v[32:35], v[52:55], v[16:31]
	ds_read_b128 v[56:59], v140 offset:57344
	v_add_f32_e64 v62, v154, v62
	v_add_f32_e64 v63, v155, v63
	v_add_f32_e64 v60, v152, v60
	v_add_f32_e64 v61, v153, v61
	v_pk_add_f32 v[130:131], v[158:159], v[62:63]
	v_pk_add_f32 v[128:129], v[156:157], v[60:61]
	s_waitcnt lgkmcnt(3)
	v_mfma_f32_32x32x16_bf16 v[0:15], v[36:39], v[52:55], v[0:15]
	ds_read_b128 v[32:35], v140 offset:61440
	s_waitcnt lgkmcnt(3)
	v_mfma_f32_32x32x16_bf16 v[80:95], v[40:43], v[44:47], v[80:95]
	v_add_u32_e32 v60, s48, v209
	ds_read_b128 v[36:39], v60 offset:49152
	v_cvt_pk_bf16_f32 v52, v152, v153
	v_cvt_pk_bf16_f32 v53, v154, v155
	v_cvt_pk_bf16_f32 v54, v156, v157
	v_cvt_pk_bf16_f32 v55, v158, v159
	s_waitcnt lgkmcnt(3)
	v_mfma_f32_32x32x16_bf16 v[64:79], v[48:51], v[44:47], v[64:79]
	ds_read_b128 v[40:43], v60 offset:53248
	s_waitcnt lgkmcnt(3)
	v_mfma_f32_32x32x16_bf16 v[16:31], v[56:59], v[44:47], v[16:31]
	ds_read_b128 v[48:51], v60 offset:57344
	s_waitcnt lgkmcnt(3)
	v_mfma_f32_32x32x16_bf16 v[0:15], v[32:35], v[44:47], v[0:15]
	ds_read_b128 v[56:59], v60 offset:61440
	s_waitcnt lgkmcnt(3)
	v_mfma_f32_32x32x16_bf16 v[80:95], v[36:39], v[52:55], v[80:95]
	s_waitcnt lgkmcnt(2)
	v_mfma_f32_32x32x16_bf16 v[64:79], v[40:43], v[52:55], v[64:79]
	s_waitcnt lgkmcnt(1)
	v_mfma_f32_32x32x16_bf16 v[16:31], v[48:51], v[52:55], v[16:31]
	s_waitcnt lgkmcnt(0)
	v_mfma_f32_32x32x16_bf16 v[0:15], v[56:59], v[52:55], v[0:15]
	s_waitcnt vmcnt(4) lgkmcnt(0)
	s_barrier
	s_add_u32 s68, s98, 0x18000
	s_addc_u32 s69, s99, 0
	s_add_i32 s49, s49, s57
	s_mov_b32 m0, s49
	s_nop 0
	global_load_lds_dwordx4 v198, s[68:69]
	s_add_i32 m0, s49, 0x400
	s_nop 0
	global_load_lds_dwordx4 v194, s[68:69]
	s_add_u32 s44, s100, 0x80
	s_addc_u32 s45, s101, 0
	s_and_b32 s49, s20, 0xc000
	s_add_i32 s49, s58, s49
	s_add_i32 m0, s49, 0xc000
	s_nop 0
	global_load_lds_dwordx4 v196, s[44:45]
	s_add_i32 m0, s49, 0xc400
	s_nop 0
	global_load_lds_dwordx4 v192, s[44:45]
	s_add_i32 s48, s48, 0xc000
	s_add_i32 s44, s41, 1
	s_cmp_lg_u32 s41, 2
	s_cselect_b32 s41, s44, 0
	s_lshl_b32 s44, s41, 14
	s_add_i32 s44, s44, 0
	v_exp_f32_e32 v144, v112
	ds_read_b128 v[32:35], v205
	ds_read_b128 v[36:39], v205 offset:8192
	s_waitcnt lgkmcnt(1)
	v_mfma_f32_32x32x16_bf16 v[48:63], v[32:35], v[160:163], 0
	ds_read_b128 v[132:135], v211
	ds_read_b128 v[136:139], v211 offset:8192
	ds_read_b128 v[140:143], v212
	v_exp_f32_e32 v145, v113
	v_exp_f32_e32 v146, v114
	v_exp_f32_e32 v147, v115
	ds_read_b128 v[112:115], v212 offset:8192
	s_waitcnt lgkmcnt(4)
	v_mfma_f32_32x32x16_bf16 v[32:47], v[36:39], v[160:163], 0
	v_exp_f32_e32 v148, v116
	v_exp_f32_e32 v149, v117
	v_exp_f32_e32 v150, v118
	v_exp_f32_e32 v151, v119
	s_waitcnt lgkmcnt(3)
	v_mfma_f32_32x32x16_bf16 v[48:63], v[132:135], v[164:167], v[48:63]
	ds_read_b128 v[116:119], v213
	v_exp_f32_e32 v152, v120
	v_exp_f32_e32 v153, v121
	v_exp_f32_e32 v154, v122
	v_exp_f32_e32 v155, v123
	s_waitcnt lgkmcnt(3)
	v_mfma_f32_32x32x16_bf16 v[32:47], v[136:139], v[164:167], v[32:47]
	ds_read_b128 v[120:123], v213 offset:8192
	v_exp_f32_e32 v156, v124
	v_exp_f32_e32 v157, v125
	v_exp_f32_e32 v158, v126
	v_exp_f32_e32 v159, v127
	s_waitcnt lgkmcnt(3)
	v_mfma_f32_32x32x16_bf16 v[48:63], v[140:143], v[168:171], v[48:63]
	v_add_u32_e32 v132, s48, v206
	ds_read_b128 v[124:127], v132 offset:16384
	v_exp_f32_e32 v136, v96
	v_exp_f32_e32 v137, v97
	v_exp_f32_e32 v138, v98
	v_exp_f32_e32 v139, v99
	s_waitcnt lgkmcnt(3)
	v_mfma_f32_32x32x16_bf16 v[32:47], v[112:115], v[168:171], v[32:47]
	ds_read_b128 v[96:99], v132 offset:20480
	v_exp_f32_e32 v140, v100
	v_exp_f32_e32 v141, v101
	v_exp_f32_e32 v142, v102
	v_exp_f32_e32 v143, v103
	s_waitcnt lgkmcnt(3)
	v_mfma_f32_32x32x16_bf16 v[48:63], v[116:119], v[172:175], v[48:63]
	ds_read_b128 v[100:103], v132 offset:24576
	v_exp_f32_e32 v178, v104
	v_exp_f32_e32 v179, v105
	v_exp_f32_e32 v180, v106
	v_exp_f32_e32 v181, v107
	s_waitcnt lgkmcnt(3)
	v_mfma_f32_32x32x16_bf16 v[32:47], v[120:123], v[172:175], v[32:47]
	ds_read_b128 v[104:107], v132 offset:28672
	v_exp_f32_e32 v182, v108
	v_exp_f32_e32 v183, v109
	v_exp_f32_e32 v184, v110
	v_exp_f32_e32 v185, v111
	v_cvt_pk_bf16_f32 v108, v144, v145
	v_cvt_pk_bf16_f32 v109, v146, v147
	v_cvt_pk_bf16_f32 v110, v148, v149
	v_cvt_pk_bf16_f32 v111, v150, v151
	s_nop 1
	s_waitcnt lgkmcnt(3)
	v_mfma_f32_32x32x16_bf16 v[80:95], v[124:127], v[108:111], v[80:95]
	v_xad_u32 v186, v206, 32, s48
	ds_read_b128 v[112:115], v186 offset:16384
	v_cvt_pk_bf16_f32 v116, v152, v153
	v_cvt_pk_bf16_f32 v117, v154, v155
	v_cvt_pk_bf16_f32 v118, v156, v157
	v_cvt_pk_bf16_f32 v119, v158, v159
	s_waitcnt lgkmcnt(3)
	v_mfma_f32_32x32x16_bf16 v[64:79], v[96:99], v[108:111], v[64:79]
	ds_read_b128 v[120:123], v186 offset:20480
	v_pk_add_f32 v[126:127], v[150:151], v[146:147]
	v_pk_add_f32 v[124:125], v[148:149], v[144:145]
	s_waitcnt lgkmcnt(3)
	v_mfma_f32_32x32x16_bf16 v[16:31], v[100:103], v[108:111], v[16:31]
	ds_read_b128 v[132:135], v186 offset:24576
	v_add_f32_e64 v98, v154, v126
	v_add_f32_e64 v99, v155, v127
	v_add_f32_e64 v96, v152, v124
	v_add_f32_e64 v97, v153, v125
	v_pk_add_f32 v[98:99], v[158:159], v[98:99]
	v_pk_add_f32 v[96:97], v[156:157], v[96:97]
	s_waitcnt lgkmcnt(3)
	v_mfma_f32_32x32x16_bf16 v[0:15], v[104:107], v[108:111], v[0:15]
	ds_read_b128 v[100:103], v186 offset:28672
	s_waitcnt lgkmcnt(3)
	v_mfma_f32_32x32x16_bf16 v[80:95], v[112:115], v[116:119], v[80:95]
	v_xad_u32 v124, v206, 64, s48
	ds_read_b128 v[104:107], v124 offset:16384
	v_cvt_pk_bf16_f32 v108, v136, v137
	v_cvt_pk_bf16_f32 v109, v138, v139
	v_cvt_pk_bf16_f32 v110, v140, v141
	v_cvt_pk_bf16_f32 v111, v142, v143
	s_waitcnt lgkmcnt(3)
	v_mfma_f32_32x32x16_bf16 v[64:79], v[120:123], v[116:119], v[64:79]
	ds_read_b128 v[112:115], v124 offset:20480
	v_add_f32_e64 v98, v138, v98
	v_add_f32_e64 v99, v139, v99
	v_add_f32_e64 v96, v136, v96
	v_add_f32_e64 v97, v137, v97
	v_pk_add_f32 v[98:99], v[142:143], v[98:99]
	v_pk_add_f32 v[96:97], v[140:141], v[96:97]
	s_waitcnt lgkmcnt(3)
	v_mfma_f32_32x32x16_bf16 v[16:31], v[132:135], v[116:119], v[16:31]
	ds_read_b128 v[120:123], v124 offset:24576
	v_add_f32_e64 v98, v180, v98
	v_add_f32_e64 v99, v181, v99
	v_add_f32_e64 v96, v178, v96
	v_add_f32_e64 v97, v179, v97
	v_pk_add_f32 v[98:99], v[184:185], v[98:99]
	v_pk_add_f32 v[96:97], v[182:183], v[96:97]
	s_waitcnt lgkmcnt(3)
	v_mfma_f32_32x32x16_bf16 v[0:15], v[100:103], v[116:119], v[0:15]
	ds_read_b128 v[124:127], v124 offset:28672
	s_waitcnt lgkmcnt(3)
	v_mfma_f32_32x32x16_bf16 v[80:95], v[104:107], v[108:111], v[80:95]
	v_add_u32_e32 v132, s48, v209
	ds_read_b128 v[100:103], v132 offset:16384
	v_cvt_pk_bf16_f32 v116, v178, v179
	v_cvt_pk_bf16_f32 v117, v180, v181
	v_cvt_pk_bf16_f32 v118, v182, v183
	v_cvt_pk_bf16_f32 v119, v184, v185
	s_waitcnt lgkmcnt(3)
	v_mfma_f32_32x32x16_bf16 v[64:79], v[112:115], v[108:111], v[64:79]
	ds_read_b128 v[104:107], v132 offset:20480
	s_waitcnt lgkmcnt(3)
	v_mfma_f32_32x32x16_bf16 v[16:31], v[120:123], v[108:111], v[16:31]
	ds_read_b128 v[112:115], v132 offset:24576
	s_waitcnt lgkmcnt(3)
	v_mfma_f32_32x32x16_bf16 v[0:15], v[124:127], v[108:111], v[0:15]
	ds_read_b128 v[120:123], v132 offset:28672
	s_waitcnt lgkmcnt(3)
	v_mfma_f32_32x32x16_bf16 v[80:95], v[100:103], v[116:119], v[80:95]
	s_waitcnt lgkmcnt(2)
	v_mfma_f32_32x32x16_bf16 v[64:79], v[104:107], v[116:119], v[64:79]
	s_waitcnt lgkmcnt(1)
	v_mfma_f32_32x32x16_bf16 v[16:31], v[112:115], v[116:119], v[16:31]
	s_waitcnt lgkmcnt(0)
	v_mfma_f32_32x32x16_bf16 v[0:15], v[120:123], v[116:119], v[0:15]
	s_waitcnt vmcnt(4) lgkmcnt(0)
	v_add_f32_e32 v100, v128, v129
	v_add_f32_e32 v101, v130, v131
	v_add_f32_e32 v100, v100, v101
	v_add_f32_e32 v96, v96, v97
	v_add_f32_e32 v97, v98, v99
	s_barrier
	v_add_f32_e32 v100, v177, v100
	v_add_f32_e32 v96, v96, v97
	v_add_f32_e32 v177, v100, v96
	s_add_i32 s21, s21, 2
	s_addk_i32 s15, 0x80
	s_add_i32 s20, s20, 0x8000
	s_add_u32 s98, s98, 0x30000
	s_addc_u32 s99, s99, 0
	s_add_u32 s100, s100, 0x100
	s_addc_u32 s101, s101, 0
	s_cmp_lt_u32 s21, 56
	s_cbranch_scc1 .Lst0_u3
	s_cmp_lt_u32 s21, 60
	s_cbranch_scc1 .Lst0_single

.Lst1_single:
	s_lshl_b32 s49, s48, 14
	s_add_i32 s49, s58, s49
	s_mov_b32 m0, s49
	s_nop 0
	global_load_lds_dwordx4 v198, s[98:99]
	s_add_i32 m0, s49, 0x400
	s_nop 0
	global_load_lds_dwordx4 v194, s[98:99]
	s_add_i32 s49, s46, 0xffffc000
	s_and_b32 s49, s49, 0xc000
	s_add_i32 s49, s58, s49
	s_add_i32 m0, s49, 0xc000
	s_nop 0
	global_load_lds_dwordx4 v196, s[100:101]
	s_add_i32 m0, s49, 0xc400
	s_add_i32 s44, s48, 1
	global_load_lds_dwordx4 v192, s[100:101]
	s_cmp_lg_u32 s48, 2
	s_cselect_b32 s48, s44, 0
	s_lshl_b32 s44, s48, 14
	s_and_b32 s49, s46, 0xc000
	s_add_i32 s68, s44, 0
	s_add_i32 s44, s49, 0
	v_add_u32_e32 v156, s44, v206
	ds_read_b128 v[140:143], v156 offset:49152
	ds_read_b128 v[148:151], v156 offset:53248
	ds_read_b128 v[152:155], v156 offset:57344
	ds_read_b128 v[156:159], v156 offset:61440
	s_waitcnt lgkmcnt(3)
	v_mfma_f32_32x32x16_bf16 v[80:95], v[140:143], v[144:147], v[80:95]
	v_xad_u32 v177, v206, 32, s44
	ds_read_b128 v[140:143], v177 offset:49152
	s_waitcnt lgkmcnt(3)
	v_mfma_f32_32x32x16_bf16 v[64:79], v[148:151], v[144:147], v[64:79]
	ds_read_b128 v[148:151], v177 offset:53248
	s_waitcnt lgkmcnt(3)
	v_mfma_f32_32x32x16_bf16 v[16:31], v[152:155], v[144:147], v[16:31]
	ds_read_b128 v[152:155], v177 offset:57344
	s_waitcnt lgkmcnt(3)
	v_mfma_f32_32x32x16_bf16 v[0:15], v[156:159], v[144:147], v[0:15]
	ds_read_b128 v[144:147], v177 offset:61440
	s_waitcnt lgkmcnt(3)
	v_mfma_f32_32x32x16_bf16 v[80:95], v[140:143], v[128:131], v[80:95]
	v_xad_u32 v156, v206, 64, s44
	ds_read_b128 v[140:143], v156 offset:49152
	s_waitcnt lgkmcnt(3)
	v_mfma_f32_32x32x16_bf16 v[64:79], v[148:151], v[128:131], v[64:79]
	ds_read_b128 v[148:151], v156 offset:53248
	s_waitcnt lgkmcnt(3)
	v_mfma_f32_32x32x16_bf16 v[16:31], v[152:155], v[128:131], v[16:31]
	ds_read_b128 v[152:155], v156 offset:57344
	s_waitcnt lgkmcnt(3)
	v_mfma_f32_32x32x16_bf16 v[0:15], v[144:147], v[128:131], v[0:15]
	ds_read_b128 v[128:131], v156 offset:61440
	s_waitcnt lgkmcnt(3)
	v_mfma_f32_32x32x16_bf16 v[80:95], v[140:143], v[132:135], v[80:95]
	v_add_u32_e32 v156, s44, v209
	ds_read_b128 v[140:143], v156 offset:49152
	s_waitcnt lgkmcnt(3)
	v_mfma_f32_32x32x16_bf16 v[64:79], v[148:151], v[132:135], v[64:79]
	ds_read_b128 v[144:147], v156 offset:53248
	s_waitcnt lgkmcnt(3)
	v_mfma_f32_32x32x16_bf16 v[16:31], v[152:155], v[132:135], v[16:31]
	ds_read_b128 v[148:151], v156 offset:57344
	s_waitcnt lgkmcnt(3)
	v_mfma_f32_32x32x16_bf16 v[0:15], v[128:131], v[132:135], v[0:15]
	ds_read_b128 v[128:131], v156 offset:61440
	s_waitcnt lgkmcnt(3)
	v_mfma_f32_32x32x16_bf16 v[80:95], v[140:143], v[136:139], v[80:95]
	v_add_u32_e32 v140, s68, v205
	ds_read_b128 v[132:135], v140
	s_waitcnt lgkmcnt(3)
	v_mfma_f32_32x32x16_bf16 v[64:79], v[144:147], v[136:139], v[64:79]
	ds_read_b128 v[140:143], v140 offset:8192
	s_waitcnt lgkmcnt(3)
	v_mfma_f32_32x32x16_bf16 v[16:31], v[148:151], v[136:139], v[16:31]
	v_xad_u32 v144, v205, 32, s68
	ds_read_b128 v[176:179], v144
	s_waitcnt lgkmcnt(3)
	v_mfma_f32_32x32x16_bf16 v[0:15], v[128:131], v[136:139], v[0:15]
	ds_read_b128 v[182:185], v144 offset:8192
	s_waitcnt lgkmcnt(3)
	v_mfma_f32_32x32x16_bf16 v[144:159], v[132:135], v[160:163], 0
	v_xad_u32 v216, v205, 64, s68
	ds_read_b128 v[186:189], v216
	v_exp_f32_e32 v220, v112
	v_exp_f32_e32 v221, v113
	v_exp_f32_e32 v222, v114
	v_exp_f32_e32 v223, v115
	s_waitcnt lgkmcnt(3)
	v_mfma_f32_32x32x16_bf16 v[128:143], v[140:143], v[160:163], 0
	ds_read_b128 v[216:219], v216 offset:8192
	v_exp_f32_e32 v224, v116
	v_exp_f32_e32 v225, v117
	v_exp_f32_e32 v226, v118
	v_exp_f32_e32 v227, v119
	s_waitcnt lgkmcnt(3)
	v_mfma_f32_32x32x16_bf16 v[144:159], v[176:179], v[164:167], v[144:159]
	v_add_u32_e32 v181, s68, v213
	ds_read_b128 v[116:119], v181
	v_exp_f32_e32 v228, v120
	v_exp_f32_e32 v229, v121
	v_exp_f32_e32 v230, v122
	v_exp_f32_e32 v231, v123
	v_cvt_pk_bf16_f32 v112, v220, v221
	v_cvt_pk_bf16_f32 v113, v222, v223
	v_cvt_pk_bf16_f32 v114, v224, v225
	v_cvt_pk_bf16_f32 v115, v226, v227
	v_pk_add_f32 v[122:123], v[226:227], v[222:223]
	v_pk_add_f32 v[120:121], v[224:225], v[220:221]
	s_waitcnt lgkmcnt(3)
	v_mfma_f32_32x32x16_bf16 v[128:143], v[182:185], v[164:167], v[128:143]
	ds_read_b128 v[176:179], v181 offset:8192
	v_exp_f32_e32 v124, v124
	v_exp_f32_e32 v125, v125
	v_exp_f32_e32 v126, v126
	v_exp_f32_e32 v127, v127
	s_waitcnt lgkmcnt(3)
	v_mfma_f32_32x32x16_bf16 v[144:159], v[186:189], v[168:171], v[144:159]
	v_add_f32_e64 v122, v230, v122
	v_add_f32_e64 v123, v231, v123
	v_add_f32_e64 v120, v228, v120
	v_add_f32_e64 v121, v229, v121
	v_exp_f32_e32 v182, v96
	v_exp_f32_e32 v183, v97
	v_exp_f32_e32 v184, v98
	v_exp_f32_e32 v185, v99
	v_cvt_pk_bf16_f32 v96, v228, v229
	v_cvt_pk_bf16_f32 v97, v230, v231
	v_cvt_pk_bf16_f32 v98, v124, v125
	v_cvt_pk_bf16_f32 v99, v126, v127
	v_pk_add_f32 v[122:123], v[126:127], v[122:123]
	v_pk_add_f32 v[120:121], v[124:125], v[120:121]
	s_waitcnt lgkmcnt(2)
	v_mfma_f32_32x32x16_bf16 v[128:143], v[216:219], v[168:171], v[128:143]
	v_exp_f32_e32 v124, v100
	v_exp_f32_e32 v125, v101
	v_exp_f32_e32 v126, v102
	v_exp_f32_e32 v127, v103
	s_waitcnt lgkmcnt(1)
	v_mfma_f32_32x32x16_bf16 v[144:159], v[116:119], v[172:175], v[144:159]
	v_exp_f32_e32 v186, v104
	v_exp_f32_e32 v187, v105
	v_exp_f32_e32 v188, v106
	v_exp_f32_e32 v189, v107
	v_pk_add_f32 v[106:107], v[184:185], v[122:123]
	v_pk_add_f32 v[104:105], v[182:183], v[120:121]
	v_cvt_pk_bf16_f32 v100, v182, v183
	v_cvt_pk_bf16_f32 v101, v184, v185
	v_cvt_pk_bf16_f32 v102, v124, v125
	v_cvt_pk_bf16_f32 v103, v126, v127
	v_pk_add_f32 v[118:119], v[126:127], v[106:107]
	v_pk_add_f32 v[116:117], v[124:125], v[104:105]
	s_waitcnt lgkmcnt(0)
	v_mfma_f32_32x32x16_bf16 v[128:143], v[176:179], v[172:175], v[128:143]
	v_exp_f32_e32 v120, v108
	v_exp_f32_e32 v121, v109
	v_exp_f32_e32 v122, v110
	v_exp_f32_e32 v123, v111
	v_pk_add_f32 v[110:111], v[188:189], v[118:119]
	v_pk_add_f32 v[108:109], v[186:187], v[116:117]
	v_cvt_pk_bf16_f32 v104, v186, v187
	v_cvt_pk_bf16_f32 v105, v188, v189
	v_cvt_pk_bf16_f32 v106, v120, v121
	v_cvt_pk_bf16_f32 v107, v122, v123
	v_pk_add_f32 v[178:179], v[122:123], v[110:111]
	v_pk_add_f32 v[176:177], v[120:121], v[108:109]
	s_waitcnt vmcnt(4) lgkmcnt(0)
	s_barrier
	s_add_u32 s70, s98, 0x18000
	s_addc_u32 s71, s99, 0
	s_add_i32 s68, s68, s57
	s_mov_b32 m0, s68
	s_nop 0
	global_load_lds_dwordx4 v198, s[70:71]
	s_add_i32 m0, s68, 0x400
	s_nop 0
	global_load_lds_dwordx4 v194, s[70:71]
	s_add_u32 s2, s100, 0x80
	s_addc_u32 s3, s101, 0
	s_add_i32 s49, s58, s49
	s_add_i32 m0, s49, 0xc000
	s_nop 0
	global_load_lds_dwordx4 v196, s[2:3]
	s_add_i32 m0, s49, 0xc400
	s_nop 0
	global_load_lds_dwordx4 v192, s[2:3]
	s_add_i32 s2, s46, 0xffff4000
	s_add_i32 s3, s48, 1
	s_cmp_lg_u32 s48, 2
	s_cselect_b32 s48, s3, 0
	s_and_b32 s2, s2, 0xc000
	s_add_i32 s2, s2, 0
	s_lshl_b32 s3, s48, 14
	v_add_u32_e32 v124, s2, v206
	ds_read_b128 v[108:111], v124 offset:49152
	ds_read_b128 v[116:119], v124 offset:53248
	ds_read_b128 v[120:123], v124 offset:57344
	ds_read_b128 v[124:127], v124 offset:61440
	s_waitcnt lgkmcnt(3)
	v_mfma_f32_32x32x16_bf16 v[80:95], v[108:111], v[112:115], v[80:95]
	v_xad_u32 v182, v206, 32, s2
	ds_read_b128 v[108:111], v182 offset:49152
	s_add_i32 s3, s3, 0
	s_waitcnt lgkmcnt(3)
	v_mfma_f32_32x32x16_bf16 v[64:79], v[116:119], v[112:115], v[64:79]
	ds_read_b128 v[116:119], v182 offset:53248
	s_waitcnt lgkmcnt(3)
	v_mfma_f32_32x32x16_bf16 v[16:31], v[120:123], v[112:115], v[16:31]
	ds_read_b128 v[120:123], v182 offset:57344
	s_waitcnt lgkmcnt(3)
	v_mfma_f32_32x32x16_bf16 v[0:15], v[124:127], v[112:115], v[0:15]
	ds_read_b128 v[112:115], v182 offset:61440
	s_waitcnt lgkmcnt(3)
	v_mfma_f32_32x32x16_bf16 v[80:95], v[108:111], v[96:99], v[80:95]
	v_xad_u32 v124, v206, 64, s2
	ds_read_b128 v[108:111], v124 offset:49152
	s_waitcnt lgkmcnt(3)
	v_mfma_f32_32x32x16_bf16 v[64:79], v[116:119], v[96:99], v[64:79]
	ds_read_b128 v[116:119], v124 offset:53248
	s_waitcnt lgkmcnt(3)
	v_mfma_f32_32x32x16_bf16 v[16:31], v[120:123], v[96:99], v[16:31]
	ds_read_b128 v[120:123], v124 offset:57344
	s_waitcnt lgkmcnt(3)
	v_mfma_f32_32x32x16_bf16 v[0:15], v[112:115], v[96:99], v[0:15]
	ds_read_b128 v[96:99], v124 offset:61440
	s_waitcnt lgkmcnt(3)
	v_mfma_f32_32x32x16_bf16 v[80:95], v[108:111], v[100:103], v[80:95]
	v_add_u32_e32 v124, s2, v209
	ds_read_b128 v[108:111], v124 offset:49152
	s_waitcnt lgkmcnt(3)
	v_mfma_f32_32x32x16_bf16 v[64:79], v[116:119], v[100:103], v[64:79]
	ds_read_b128 v[112:115], v124 offset:53248
	s_waitcnt lgkmcnt(3)
	v_mfma_f32_32x32x16_bf16 v[16:31], v[120:123], v[100:103], v[16:31]
	ds_read_b128 v[116:119], v124 offset:57344
	s_waitcnt lgkmcnt(3)
	v_mfma_f32_32x32x16_bf16 v[0:15], v[96:99], v[100:103], v[0:15]
	ds_read_b128 v[120:123], v124 offset:61440
	s_waitcnt lgkmcnt(3)
	v_mfma_f32_32x32x16_bf16 v[80:95], v[108:111], v[104:107], v[80:95]
	v_add_u32_e32 v100, s3, v205
	ds_read_b128 v[96:99], v100
	s_waitcnt lgkmcnt(3)
	v_mfma_f32_32x32x16_bf16 v[64:79], v[112:115], v[104:107], v[64:79]
	ds_read_b128 v[100:103], v100 offset:8192
	s_waitcnt lgkmcnt(3)
	v_mfma_f32_32x32x16_bf16 v[16:31], v[116:119], v[104:107], v[16:31]
	v_xad_u32 v108, v205, 32, s3
	ds_read_b128 v[182:185], v108
	s_waitcnt lgkmcnt(3)
	v_mfma_f32_32x32x16_bf16 v[0:15], v[120:123], v[104:107], v[0:15]
	ds_read_b128 v[186:189], v108 offset:8192
	s_waitcnt lgkmcnt(3)
	v_mfma_f32_32x32x16_bf16 v[112:127], v[96:99], v[160:163], 0
	v_xad_u32 v104, v205, 64, s3
	ds_read_b128 v[216:219], v104
	v_exp_f32_e32 v224, v144
	v_exp_f32_e32 v225, v145
	v_exp_f32_e32 v226, v146
	v_exp_f32_e32 v227, v147
	ds_read_b128 v[220:223], v104 offset:8192
	s_waitcnt lgkmcnt(4)
	v_mfma_f32_32x32x16_bf16 v[96:111], v[100:103], v[160:163], 0
	v_exp_f32_e32 v228, v148
	v_exp_f32_e32 v229, v149
	v_exp_f32_e32 v230, v150
	v_exp_f32_e32 v231, v151
	s_waitcnt lgkmcnt(3)
	v_mfma_f32_32x32x16_bf16 v[112:127], v[182:185], v[164:167], v[112:127]
	v_add_u32_e32 v181, s3, v213
	ds_read_b128 v[148:151], v181
	v_exp_f32_e32 v232, v152
	v_exp_f32_e32 v233, v153
	v_exp_f32_e32 v234, v154
	v_exp_f32_e32 v235, v155
	v_cvt_pk_bf16_f32 v144, v224, v225
	v_cvt_pk_bf16_f32 v145, v226, v227
	v_cvt_pk_bf16_f32 v146, v228, v229
	v_cvt_pk_bf16_f32 v147, v230, v231
	v_pk_add_f32 v[154:155], v[230:231], v[226:227]
	v_pk_add_f32 v[152:153], v[228:229], v[224:225]
	s_waitcnt lgkmcnt(3)
	v_mfma_f32_32x32x16_bf16 v[96:111], v[186:189], v[164:167], v[96:111]
	ds_read_b128 v[182:185], v181 offset:8192
	v_exp_f32_e32 v156, v156
	v_exp_f32_e32 v157, v157
	v_exp_f32_e32 v158, v158
	v_exp_f32_e32 v159, v159
	s_waitcnt lgkmcnt(3)
	v_mfma_f32_32x32x16_bf16 v[112:127], v[216:219], v[168:171], v[112:127]
	v_add_f32_e64 v154, v234, v154
	v_add_f32_e64 v155, v235, v155
	v_add_f32_e64 v152, v232, v152
	v_add_f32_e64 v153, v233, v153
	v_exp_f32_e32 v186, v128
	v_exp_f32_e32 v187, v129
	v_exp_f32_e32 v188, v130
	v_exp_f32_e32 v189, v131
	v_cvt_pk_bf16_f32 v128, v232, v233
	v_cvt_pk_bf16_f32 v129, v234, v235
	v_cvt_pk_bf16_f32 v130, v156, v157
	v_cvt_pk_bf16_f32 v131, v158, v159
	v_pk_add_f32 v[154:155], v[158:159], v[154:155]
	v_pk_add_f32 v[152:153], v[156:157], v[152:153]
	s_waitcnt lgkmcnt(2)
	v_mfma_f32_32x32x16_bf16 v[96:111], v[220:223], v[168:171], v[96:111]
	v_exp_f32_e32 v156, v132
	v_exp_f32_e32 v157, v133
	v_exp_f32_e32 v158, v134
	v_exp_f32_e32 v159, v135
	s_waitcnt lgkmcnt(1)
	v_mfma_f32_32x32x16_bf16 v[112:127], v[148:151], v[172:175], v[112:127]
	v_exp_f32_e32 v216, v136
	v_exp_f32_e32 v217, v137
	v_exp_f32_e32 v218, v138
	v_exp_f32_e32 v219, v139
	v_pk_add_f32 v[138:139], v[188:189], v[154:155]
	v_pk_add_f32 v[136:137], v[186:187], v[152:153]
	v_cvt_pk_bf16_f32 v132, v186, v187
	v_cvt_pk_bf16_f32 v133, v188, v189
	v_cvt_pk_bf16_f32 v134, v156, v157
	v_cvt_pk_bf16_f32 v135, v158, v159
	v_pk_add_f32 v[150:151], v[158:159], v[138:139]
	v_pk_add_f32 v[148:149], v[156:157], v[136:137]
	s_waitcnt lgkmcnt(0)
	v_mfma_f32_32x32x16_bf16 v[96:111], v[182:185], v[172:175], v[96:111]
	v_exp_f32_e32 v152, v140
	v_exp_f32_e32 v153, v141
	v_exp_f32_e32 v154, v142
	v_exp_f32_e32 v155, v143
	v_pk_add_f32 v[142:143], v[218:219], v[150:151]
	v_pk_add_f32 v[140:141], v[216:217], v[148:149]
	v_cvt_pk_bf16_f32 v136, v216, v217
	v_cvt_pk_bf16_f32 v137, v218, v219
	v_cvt_pk_bf16_f32 v138, v152, v153
	v_cvt_pk_bf16_f32 v139, v154, v155
	v_pk_add_f32 v[142:143], v[154:155], v[142:143]
	v_pk_add_f32 v[140:141], v[152:153], v[140:141]
	s_waitcnt vmcnt(4) lgkmcnt(0)
	v_add_f32_e32 v148, v176, v177
	v_add_f32_e32 v149, v178, v179
	v_add_f32_e32 v148, v148, v149
	v_add_f32_e32 v140, v140, v141
	v_add_f32_e32 v141, v142, v143
	s_barrier
	v_add_f32_e32 v148, v180, v148
	v_add_f32_e32 v140, v140, v141
	v_add_f32_e32 v180, v148, v140
	s_add_i32 s47, s47, 2
	s_addk_i32 s41, 0x80
	s_add_i32 s46, s46, 0x8000
	s_add_u32 s98, s98, 0x30000
	s_addc_u32 s99, s99, 0
	s_add_u32 s100, s100, 0x100
	s_addc_u32 s101, s101, 0
	s_cmp_lt_u32 s47, 60
	s_cbranch_scc1 .Lst1_loop
	s_branch .Lst1_exit
.Lst1_u3:
	s_lshl_b32 s49, s48, 14
	s_add_i32 s49, s58, s49
	s_mov_b32 m0, s49
	s_nop 0
	global_load_lds_dwordx4 v198, s[98:99]
	s_add_i32 m0, s49, 0x400
	s_nop 0
	global_load_lds_dwordx4 v194, s[98:99]
	s_add_i32 s49, s46, 0xffffc000
	s_and_b32 s49, s49, 0xc000
	s_add_i32 s49, s58, s49
	s_add_i32 m0, s49, 0xc000
	s_nop 0
	global_load_lds_dwordx4 v196, s[100:101]
	s_add_i32 m0, s49, 0xc400
	s_add_i32 s44, s48, 1
	global_load_lds_dwordx4 v192, s[100:101]
	s_cmp_lg_u32 s48, 2
	s_cselect_b32 s48, s44, 0
	s_lshl_b32 s44, s48, 14
	s_and_b32 s49, s46, 0xc000
	s_add_i32 s68, s44, 0
	s_add_i32 s44, s49, 0
	v_add_u32_e32 v156, s44, v206
	ds_read_b128 v[140:143], v156 offset:49152
	ds_read_b128 v[148:151], v156 offset:53248
	ds_read_b128 v[152:155], v156 offset:57344
	ds_read_b128 v[156:159], v156 offset:61440
	s_waitcnt lgkmcnt(3)
	v_mfma_f32_32x32x16_bf16 v[80:95], v[140:143], v[144:147], v[80:95]
	v_xad_u32 v177, v206, 32, s44
	ds_read_b128 v[140:143], v177 offset:49152
	s_waitcnt lgkmcnt(3)
	v_mfma_f32_32x32x16_bf16 v[64:79], v[148:151], v[144:147], v[64:79]
	ds_read_b128 v[148:151], v177 offset:53248
	s_waitcnt lgkmcnt(3)
	v_mfma_f32_32x32x16_bf16 v[16:31], v[152:155], v[144:147], v[16:31]
	ds_read_b128 v[152:155], v177 offset:57344
	s_waitcnt lgkmcnt(3)
	v_mfma_f32_32x32x16_bf16 v[0:15], v[156:159], v[144:147], v[0:15]
	ds_read_b128 v[144:147], v177 offset:61440
	s_waitcnt lgkmcnt(3)
	v_mfma_f32_32x32x16_bf16 v[80:95], v[140:143], v[128:131], v[80:95]
	v_xad_u32 v156, v206, 64, s44
	ds_read_b128 v[140:143], v156 offset:49152
	s_waitcnt lgkmcnt(3)
	v_mfma_f32_32x32x16_bf16 v[64:79], v[148:151], v[128:131], v[64:79]
	ds_read_b128 v[148:151], v156 offset:53248
	s_waitcnt lgkmcnt(3)
	v_mfma_f32_32x32x16_bf16 v[16:31], v[152:155], v[128:131], v[16:31]
	ds_read_b128 v[152:155], v156 offset:57344
	s_waitcnt lgkmcnt(3)
	v_mfma_f32_32x32x16_bf16 v[0:15], v[144:147], v[128:131], v[0:15]
	ds_read_b128 v[128:131], v156 offset:61440
	s_waitcnt lgkmcnt(3)
	v_mfma_f32_32x32x16_bf16 v[80:95], v[140:143], v[132:135], v[80:95]
	v_add_u32_e32 v156, s44, v209
	ds_read_b128 v[140:143], v156 offset:49152
	s_waitcnt lgkmcnt(3)
	v_mfma_f32_32x32x16_bf16 v[64:79], v[148:151], v[132:135], v[64:79]
	ds_read_b128 v[144:147], v156 offset:53248
	s_waitcnt lgkmcnt(3)
	v_mfma_f32_32x32x16_bf16 v[16:31], v[152:155], v[132:135], v[16:31]
	ds_read_b128 v[148:151], v156 offset:57344
	s_waitcnt lgkmcnt(3)
	v_mfma_f32_32x32x16_bf16 v[0:15], v[128:131], v[132:135], v[0:15]
	ds_read_b128 v[128:131], v156 offset:61440
	s_waitcnt lgkmcnt(3)
	v_mfma_f32_32x32x16_bf16 v[80:95], v[140:143], v[136:139], v[80:95]
	ds_read_b128 v[132:135], v205 offset:16384
	s_waitcnt lgkmcnt(3)
	v_mfma_f32_32x32x16_bf16 v[64:79], v[144:147], v[136:139], v[64:79]
	ds_read_b128 v[140:143], v205 offset:24576
	s_waitcnt lgkmcnt(3)
	v_mfma_f32_32x32x16_bf16 v[16:31], v[148:151], v[136:139], v[16:31]
	ds_read_b128 v[176:179], v211 offset:16384
	s_waitcnt lgkmcnt(3)
	v_mfma_f32_32x32x16_bf16 v[0:15], v[128:131], v[136:139], v[0:15]
	ds_read_b128 v[182:185], v211 offset:24576
	s_waitcnt lgkmcnt(3)
	v_mfma_f32_32x32x16_bf16 v[144:159], v[132:135], v[160:163], 0
	ds_read_b128 v[186:189], v212 offset:16384
	v_exp_f32_e32 v220, v112
	v_exp_f32_e32 v221, v113
	v_exp_f32_e32 v222, v114
	v_exp_f32_e32 v223, v115
	s_waitcnt lgkmcnt(3)
	v_mfma_f32_32x32x16_bf16 v[128:143], v[140:143], v[160:163], 0
	ds_read_b128 v[216:219], v212 offset:24576
	v_exp_f32_e32 v224, v116
	v_exp_f32_e32 v225, v117
	v_exp_f32_e32 v226, v118
	v_exp_f32_e32 v227, v119
	s_waitcnt lgkmcnt(3)
	v_mfma_f32_32x32x16_bf16 v[144:159], v[176:179], v[164:167], v[144:159]
	ds_read_b128 v[116:119], v213 offset:16384
	v_exp_f32_e32 v228, v120
	v_exp_f32_e32 v229, v121
	v_exp_f32_e32 v230, v122
	v_exp_f32_e32 v231, v123
	v_cvt_pk_bf16_f32 v112, v220, v221
	v_cvt_pk_bf16_f32 v113, v222, v223
	v_cvt_pk_bf16_f32 v114, v224, v225
	v_cvt_pk_bf16_f32 v115, v226, v227
	v_pk_add_f32 v[122:123], v[226:227], v[222:223]
	v_pk_add_f32 v[120:121], v[224:225], v[220:221]
	s_waitcnt lgkmcnt(3)
	v_mfma_f32_32x32x16_bf16 v[128:143], v[182:185], v[164:167], v[128:143]
	ds_read_b128 v[176:179], v213 offset:24576
	v_exp_f32_e32 v124, v124
	v_exp_f32_e32 v125, v125
	v_exp_f32_e32 v126, v126
	v_exp_f32_e32 v127, v127
	s_waitcnt lgkmcnt(3)
	v_mfma_f32_32x32x16_bf16 v[144:159], v[186:189], v[168:171], v[144:159]
	v_add_f32_e64 v122, v230, v122
	v_add_f32_e64 v123, v231, v123
	v_add_f32_e64 v120, v228, v120
	v_add_f32_e64 v121, v229, v121
	v_exp_f32_e32 v182, v96
	v_exp_f32_e32 v183, v97
	v_exp_f32_e32 v184, v98
	v_exp_f32_e32 v185, v99
	v_cvt_pk_bf16_f32 v96, v228, v229
	v_cvt_pk_bf16_f32 v97, v230, v231
	v_cvt_pk_bf16_f32 v98, v124, v125
	v_cvt_pk_bf16_f32 v99, v126, v127
	v_pk_add_f32 v[122:123], v[126:127], v[122:123]
	v_pk_add_f32 v[120:121], v[124:125], v[120:121]
	s_waitcnt lgkmcnt(2)
	v_mfma_f32_32x32x16_bf16 v[128:143], v[216:219], v[168:171], v[128:143]
	v_exp_f32_e32 v124, v100
	v_exp_f32_e32 v125, v101
	v_exp_f32_e32 v126, v102
	v_exp_f32_e32 v127, v103
	s_waitcnt lgkmcnt(1)
	v_mfma_f32_32x32x16_bf16 v[144:159], v[116:119], v[172:175], v[144:159]
	v_exp_f32_e32 v186, v104
	v_exp_f32_e32 v187, v105
	v_exp_f32_e32 v188, v106
	v_exp_f32_e32 v189, v107
	v_pk_add_f32 v[106:107], v[184:185], v[122:123]
	v_pk_add_f32 v[104:105], v[182:183], v[120:121]
	v_cvt_pk_bf16_f32 v100, v182, v183
	v_cvt_pk_bf16_f32 v101, v184, v185
	v_cvt_pk_bf16_f32 v102, v124, v125
	v_cvt_pk_bf16_f32 v103, v126, v127
	v_pk_add_f32 v[118:119], v[126:127], v[106:107]
	v_pk_add_f32 v[116:117], v[124:125], v[104:105]
	s_waitcnt lgkmcnt(0)
	v_mfma_f32_32x32x16_bf16 v[128:143], v[176:179], v[172:175], v[128:143]
	v_exp_f32_e32 v120, v108
	v_exp_f32_e32 v121, v109
	v_exp_f32_e32 v122, v110
	v_exp_f32_e32 v123, v111
	v_pk_add_f32 v[110:111], v[188:189], v[118:119]
	v_pk_add_f32 v[108:109], v[186:187], v[116:117]
	v_cvt_pk_bf16_f32 v104, v186, v187
	v_cvt_pk_bf16_f32 v105, v188, v189
	v_cvt_pk_bf16_f32 v106, v120, v121
	v_cvt_pk_bf16_f32 v107, v122, v123
	v_pk_add_f32 v[178:179], v[122:123], v[110:111]
	v_pk_add_f32 v[176:177], v[120:121], v[108:109]
	s_waitcnt vmcnt(4) lgkmcnt(0)
	s_barrier
	s_add_u32 s70, s98, 0x18000
	s_addc_u32 s71, s99, 0
	s_add_i32 s68, s68, s57
	s_mov_b32 m0, s68
	s_nop 0
	global_load_lds_dwordx4 v198, s[70:71]
	s_add_i32 m0, s68, 0x400
	s_nop 0
	global_load_lds_dwordx4 v194, s[70:71]
	s_add_u32 s2, s100, 0x80
	s_addc_u32 s3, s101, 0
	s_add_i32 s49, s58, s49
	s_add_i32 m0, s49, 0xc000
	s_nop 0
	global_load_lds_dwordx4 v196, s[2:3]
	s_add_i32 m0, s49, 0xc400
	s_nop 0
	global_load_lds_dwordx4 v192, s[2:3]
	s_add_i32 s2, s46, 0xffff4000
	s_add_i32 s3, s48, 1
	s_cmp_lg_u32 s48, 2
	s_cselect_b32 s48, s3, 0
	s_and_b32 s2, s2, 0xc000
	s_add_i32 s2, s2, 0
	s_lshl_b32 s3, s48, 14
	v_add_u32_e32 v124, s2, v206
	ds_read_b128 v[108:111], v124 offset:49152
	ds_read_b128 v[116:119], v124 offset:53248
	ds_read_b128 v[120:123], v124 offset:57344
	ds_read_b128 v[124:127], v124 offset:61440
	s_waitcnt lgkmcnt(3)
	v_mfma_f32_32x32x16_bf16 v[80:95], v[108:111], v[112:115], v[80:95]
	v_xad_u32 v182, v206, 32, s2
	ds_read_b128 v[108:111], v182 offset:49152
	s_add_i32 s3, s3, 0
	s_waitcnt lgkmcnt(3)
	v_mfma_f32_32x32x16_bf16 v[64:79], v[116:119], v[112:115], v[64:79]
	ds_read_b128 v[116:119], v182 offset:53248
	s_waitcnt lgkmcnt(3)
	v_mfma_f32_32x32x16_bf16 v[16:31], v[120:123], v[112:115], v[16:31]
	ds_read_b128 v[120:123], v182 offset:57344
	s_waitcnt lgkmcnt(3)
	v_mfma_f32_32x32x16_bf16 v[0:15], v[124:127], v[112:115], v[0:15]
	ds_read_b128 v[112:115], v182 offset:61440
	s_waitcnt lgkmcnt(3)
	v_mfma_f32_32x32x16_bf16 v[80:95], v[108:111], v[96:99], v[80:95]
	v_xad_u32 v124, v206, 64, s2
	ds_read_b128 v[108:111], v124 offset:49152
	s_waitcnt lgkmcnt(3)
	v_mfma_f32_32x32x16_bf16 v[64:79], v[116:119], v[96:99], v[64:79]
	ds_read_b128 v[116:119], v124 offset:53248
	s_waitcnt lgkmcnt(3)
	v_mfma_f32_32x32x16_bf16 v[16:31], v[120:123], v[96:99], v[16:31]
	ds_read_b128 v[120:123], v124 offset:57344
	s_waitcnt lgkmcnt(3)
	v_mfma_f32_32x32x16_bf16 v[0:15], v[112:115], v[96:99], v[0:15]
	ds_read_b128 v[96:99], v124 offset:61440
	s_waitcnt lgkmcnt(3)
	v_mfma_f32_32x32x16_bf16 v[80:95], v[108:111], v[100:103], v[80:95]
	v_add_u32_e32 v124, s2, v209
	ds_read_b128 v[108:111], v124 offset:49152
	s_waitcnt lgkmcnt(3)
	v_mfma_f32_32x32x16_bf16 v[64:79], v[116:119], v[100:103], v[64:79]
	ds_read_b128 v[112:115], v124 offset:53248
	s_waitcnt lgkmcnt(3)
	v_mfma_f32_32x32x16_bf16 v[16:31], v[120:123], v[100:103], v[16:31]
	ds_read_b128 v[116:119], v124 offset:57344
	s_waitcnt lgkmcnt(3)
	v_mfma_f32_32x32x16_bf16 v[0:15], v[96:99], v[100:103], v[0:15]
	ds_read_b128 v[120:123], v124 offset:61440
	s_waitcnt lgkmcnt(3)
	v_mfma_f32_32x32x16_bf16 v[80:95], v[108:111], v[104:107], v[80:95]
	ds_read_b128 v[96:99], v205 offset:32768
	s_waitcnt lgkmcnt(3)
	v_mfma_f32_32x32x16_bf16 v[64:79], v[112:115], v[104:107], v[64:79]
	ds_read_b128 v[100:103], v205 offset:40960
	s_waitcnt lgkmcnt(3)
	v_mfma_f32_32x32x16_bf16 v[16:31], v[116:119], v[104:107], v[16:31]
	ds_read_b128 v[182:185], v211 offset:32768
	s_waitcnt lgkmcnt(3)
	v_mfma_f32_32x32x16_bf16 v[0:15], v[120:123], v[104:107], v[0:15]
	ds_read_b128 v[186:189], v211 offset:40960
	s_waitcnt lgkmcnt(3)
	v_mfma_f32_32x32x16_bf16 v[112:127], v[96:99], v[160:163], 0
	ds_read_b128 v[216:219], v212 offset:32768
	v_exp_f32_e32 v224, v144
	v_exp_f32_e32 v225, v145
	v_exp_f32_e32 v226, v146
	v_exp_f32_e32 v227, v147
	ds_read_b128 v[220:223], v212 offset:40960
	s_waitcnt lgkmcnt(4)
	v_mfma_f32_32x32x16_bf16 v[96:111], v[100:103], v[160:163], 0
	v_exp_f32_e32 v228, v148
	v_exp_f32_e32 v229, v149
	v_exp_f32_e32 v230, v150
	v_exp_f32_e32 v231, v151
	s_waitcnt lgkmcnt(3)
	v_mfma_f32_32x32x16_bf16 v[112:127], v[182:185], v[164:167], v[112:127]
	ds_read_b128 v[148:151], v213 offset:32768
	v_exp_f32_e32 v232, v152
	v_exp_f32_e32 v233, v153
	v_exp_f32_e32 v234, v154
	v_exp_f32_e32 v235, v155
	v_cvt_pk_bf16_f32 v144, v224, v225
	v_cvt_pk_bf16_f32 v145, v226, v227
	v_cvt_pk_bf16_f32 v146, v228, v229
	v_cvt_pk_bf16_f32 v147, v230, v231
	v_pk_add_f32 v[154:155], v[230:231], v[226:227]
	v_pk_add_f32 v[152:153], v[228:229], v[224:225]
	s_waitcnt lgkmcnt(3)
	v_mfma_f32_32x32x16_bf16 v[96:111], v[186:189], v[164:167], v[96:111]
	ds_read_b128 v[182:185], v213 offset:40960
	v_exp_f32_e32 v156, v156
	v_exp_f32_e32 v157, v157
	v_exp_f32_e32 v158, v158
	v_exp_f32_e32 v159, v159
	s_waitcnt lgkmcnt(3)
	v_mfma_f32_32x32x16_bf16 v[112:127], v[216:219], v[168:171], v[112:127]
	v_add_f32_e64 v154, v234, v154
	v_add_f32_e64 v155, v235, v155
	v_add_f32_e64 v152, v232, v152
	v_add_f32_e64 v153, v233, v153
	v_exp_f32_e32 v186, v128
	v_exp_f32_e32 v187, v129
	v_exp_f32_e32 v188, v130
	v_exp_f32_e32 v189, v131
	v_cvt_pk_bf16_f32 v128, v232, v233
	v_cvt_pk_bf16_f32 v129, v234, v235
	v_cvt_pk_bf16_f32 v130, v156, v157
	v_cvt_pk_bf16_f32 v131, v158, v159
	v_pk_add_f32 v[154:155], v[158:159], v[154:155]
	v_pk_add_f32 v[152:153], v[156:157], v[152:153]
	s_waitcnt lgkmcnt(2)
	v_mfma_f32_32x32x16_bf16 v[96:111], v[220:223], v[168:171], v[96:111]
	v_exp_f32_e32 v156, v132
	v_exp_f32_e32 v157, v133
	v_exp_f32_e32 v158, v134
	v_exp_f32_e32 v159, v135
	s_waitcnt lgkmcnt(1)
	v_mfma_f32_32x32x16_bf16 v[112:127], v[148:151], v[172:175], v[112:127]
	v_exp_f32_e32 v216, v136
	v_exp_f32_e32 v217, v137
	v_exp_f32_e32 v218, v138
	v_exp_f32_e32 v219, v139
	v_pk_add_f32 v[138:139], v[188:189], v[154:155]
	v_pk_add_f32 v[136:137], v[186:187], v[152:153]
	v_cvt_pk_bf16_f32 v132, v186, v187
	v_cvt_pk_bf16_f32 v133, v188, v189
	v_cvt_pk_bf16_f32 v134, v156, v157
	v_cvt_pk_bf16_f32 v135, v158, v159
	v_pk_add_f32 v[150:151], v[158:159], v[138:139]
	v_pk_add_f32 v[148:149], v[156:157], v[136:137]
	s_waitcnt lgkmcnt(0)
	v_mfma_f32_32x32x16_bf16 v[96:111], v[182:185], v[172:175], v[96:111]
	v_exp_f32_e32 v152, v140
	v_exp_f32_e32 v153, v141
	v_exp_f32_e32 v154, v142
	v_exp_f32_e32 v155, v143
	v_pk_add_f32 v[142:143], v[218:219], v[150:151]
	v_pk_add_f32 v[140:141], v[216:217], v[148:149]
	v_cvt_pk_bf16_f32 v136, v216, v217
	v_cvt_pk_bf16_f32 v137, v218, v219
	v_cvt_pk_bf16_f32 v138, v152, v153
	v_cvt_pk_bf16_f32 v139, v154, v155
	v_pk_add_f32 v[142:143], v[154:155], v[142:143]
	v_pk_add_f32 v[140:141], v[152:153], v[140:141]
	s_waitcnt vmcnt(4) lgkmcnt(0)
	v_add_f32_e32 v148, v176, v177
	v_add_f32_e32 v149, v178, v179
	v_add_f32_e32 v148, v148, v149
	v_add_f32_e32 v140, v140, v141
	v_add_f32_e32 v141, v142, v143
	s_barrier
	v_add_f32_e32 v148, v180, v148
	v_add_f32_e32 v140, v140, v141
	v_add_f32_e32 v180, v148, v140
	s_add_i32 s47, s47, 2
	s_addk_i32 s41, 0x80
	s_add_i32 s46, s46, 0x8000
	s_add_u32 s98, s98, 0x30000
	s_addc_u32 s99, s99, 0
	s_add_u32 s100, s100, 0x100
	s_addc_u32 s101, s101, 0
	s_lshl_b32 s49, s48, 14
	s_add_i32 s49, s58, s49
	s_mov_b32 m0, s49
	s_nop 0
	global_load_lds_dwordx4 v198, s[98:99]
	s_add_i32 m0, s49, 0x400
	s_nop 0
	global_load_lds_dwordx4 v194, s[98:99]
	s_add_i32 s49, s46, 0xffffc000
	s_and_b32 s49, s49, 0xc000
	s_add_i32 s49, s58, s49
	s_add_i32 m0, s49, 0xc000
	s_nop 0
	global_load_lds_dwordx4 v196, s[100:101]
	s_add_i32 m0, s49, 0xc400
	s_add_i32 s44, s48, 1
	global_load_lds_dwordx4 v192, s[100:101]
	s_cmp_lg_u32 s48, 2
	s_cselect_b32 s48, s44, 0
	s_lshl_b32 s44, s48, 14
	s_and_b32 s49, s46, 0xc000
	s_add_i32 s68, s44, 0
	s_add_i32 s44, s49, 0
	v_add_u32_e32 v156, s44, v206
	ds_read_b128 v[140:143], v156 offset:49152
	ds_read_b128 v[148:151], v156 offset:53248
	ds_read_b128 v[152:155], v156 offset:57344
	ds_read_b128 v[156:159], v156 offset:61440
	s_waitcnt lgkmcnt(3)
	v_mfma_f32_32x32x16_bf16 v[80:95], v[140:143], v[144:147], v[80:95]
	v_xad_u32 v177, v206, 32, s44
	ds_read_b128 v[140:143], v177 offset:49152
	s_waitcnt lgkmcnt(3)
	v_mfma_f32_32x32x16_bf16 v[64:79], v[148:151], v[144:147], v[64:79]
	ds_read_b128 v[148:151], v177 offset:53248
	s_waitcnt lgkmcnt(3)
	v_mfma_f32_32x32x16_bf16 v[16:31], v[152:155], v[144:147], v[16:31]
	ds_read_b128 v[152:155], v177 offset:57344
	s_waitcnt lgkmcnt(3)
	v_mfma_f32_32x32x16_bf16 v[0:15], v[156:159], v[144:147], v[0:15]
	ds_read_b128 v[144:147], v177 offset:61440
	s_waitcnt lgkmcnt(3)
	v_mfma_f32_32x32x16_bf16 v[80:95], v[140:143], v[128:131], v[80:95]
	v_xad_u32 v156, v206, 64, s44
	ds_read_b128 v[140:143], v156 offset:49152
	s_waitcnt lgkmcnt(3)
	v_mfma_f32_32x32x16_bf16 v[64:79], v[148:151], v[128:131], v[64:79]
	ds_read_b128 v[148:151], v156 offset:53248
	s_waitcnt lgkmcnt(3)
	v_mfma_f32_32x32x16_bf16 v[16:31], v[152:155], v[128:131], v[16:31]
	ds_read_b128 v[152:155], v156 offset:57344
	s_waitcnt lgkmcnt(3)
	v_mfma_f32_32x32x16_bf16 v[0:15], v[144:147], v[128:131], v[0:15]
	ds_read_b128 v[128:131], v156 offset:61440
	s_waitcnt lgkmcnt(3)
	v_mfma_f32_32x32x16_bf16 v[80:95], v[140:143], v[132:135], v[80:95]
	v_add_u32_e32 v156, s44, v209
	ds_read_b128 v[140:143], v156 offset:49152
	s_waitcnt lgkmcnt(3)
	v_mfma_f32_32x32x16_bf16 v[64:79], v[148:151], v[132:135], v[64:79]
	ds_read_b128 v[144:147], v156 offset:53248
	s_waitcnt lgkmcnt(3)
	v_mfma_f32_32x32x16_bf16 v[16:31], v[152:155], v[132:135], v[16:31]
	ds_read_b128 v[148:151], v156 offset:57344
	s_waitcnt lgkmcnt(3)
	v_mfma_f32_32x32x16_bf16 v[0:15], v[128:131], v[132:135], v[0:15]
	ds_read_b128 v[128:131], v156 offset:61440
	s_waitcnt lgkmcnt(3)
	v_mfma_f32_32x32x16_bf16 v[80:95], v[140:143], v[136:139], v[80:95]
	ds_read_b128 v[132:135], v205
	s_waitcnt lgkmcnt(3)
	v_mfma_f32_32x32x16_bf16 v[64:79], v[144:147], v[136:139], v[64:79]
	ds_read_b128 v[140:143], v205 offset:8192
	s_waitcnt lgkmcnt(3)
	v_mfma_f32_32x32x16_bf16 v[16:31], v[148:151], v[136:139], v[16:31]
	ds_read_b128 v[176:179], v211
	s_waitcnt lgkmcnt(3)
	v_mfma_f32_32x32x16_bf16 v[0:15], v[128:131], v[136:139], v[0:15]
	ds_read_b128 v[182:185], v211 offset:8192
	s_waitcnt lgkmcnt(3)
	v_mfma_f32_32x32x16_bf16 v[144:159], v[132:135], v[160:163], 0
	ds_read_b128 v[186:189], v212
	v_exp_f32_e32 v220, v112
	v_exp_f32_e32 v221, v113
	v_exp_f32_e32 v222, v114
	v_exp_f32_e32 v223, v115
	s_waitcnt lgkmcnt(3)
	v_mfma_f32_32x32x16_bf16 v[128:143], v[140:143], v[160:163], 0
	ds_read_b128 v[216:219], v212 offset:8192
	v_exp_f32_e32 v224, v116
	v_exp_f32_e32 v225, v117
	v_exp_f32_e32 v226, v118
	v_exp_f32_e32 v227, v119
	s_waitcnt lgkmcnt(3)
	v_mfma_f32_32x32x16_bf16 v[144:159], v[176:179], v[164:167], v[144:159]
	ds_read_b128 v[116:119], v213
	v_exp_f32_e32 v228, v120
	v_exp_f32_e32 v229, v121
	v_exp_f32_e32 v230, v122
	v_exp_f32_e32 v231, v123
	v_cvt_pk_bf16_f32 v112, v220, v221
	v_cvt_pk_bf16_f32 v113, v222, v223
	v_cvt_pk_bf16_f32 v114, v224, v225
	v_cvt_pk_bf16_f32 v115, v226, v227
	v_pk_add_f32 v[122:123], v[226:227], v[222:223]
	v_pk_add_f32 v[120:121], v[224:225], v[220:221]
	s_waitcnt lgkmcnt(3)
	v_mfma_f32_32x32x16_bf16 v[128:143], v[182:185], v[164:167], v[128:143]
	ds_read_b128 v[176:179], v213 offset:8192
	v_exp_f32_e32 v124, v124
	v_exp_f32_e32 v125, v125
	v_exp_f32_e32 v126, v126
	v_exp_f32_e32 v127, v127
	s_waitcnt lgkmcnt(3)
	v_mfma_f32_32x32x16_bf16 v[144:159], v[186:189], v[168:171], v[144:159]
	v_add_f32_e64 v122, v230, v122
	v_add_f32_e64 v123, v231, v123
	v_add_f32_e64 v120, v228, v120
	v_add_f32_e64 v121, v229, v121
	v_exp_f32_e32 v182, v96
	v_exp_f32_e32 v183, v97
	v_exp_f32_e32 v184, v98
	v_exp_f32_e32 v185, v99
	v_cvt_pk_bf16_f32 v96, v228, v229
	v_cvt_pk_bf16_f32 v97, v230, v231
	v_cvt_pk_bf16_f32 v98, v124, v125
	v_cvt_pk_bf16_f32 v99, v126, v127
	v_pk_add_f32 v[122:123], v[126:127], v[122:123]
	v_pk_add_f32 v[120:121], v[124:125], v[120:121]
	s_waitcnt lgkmcnt(2)
	v_mfma_f32_32x32x16_bf16 v[128:143], v[216:219], v[168:171], v[128:143]
	v_exp_f32_e32 v124, v100
	v_exp_f32_e32 v125, v101
	v_exp_f32_e32 v126, v102
	v_exp_f32_e32 v127, v103
	s_waitcnt lgkmcnt(1)
	v_mfma_f32_32x32x16_bf16 v[144:159], v[116:119], v[172:175], v[144:159]
	v_exp_f32_e32 v186, v104
	v_exp_f32_e32 v187, v105
	v_exp_f32_e32 v188, v106
	v_exp_f32_e32 v189, v107
	v_pk_add_f32 v[106:107], v[184:185], v[122:123]
	v_pk_add_f32 v[104:105], v[182:183], v[120:121]
	v_cvt_pk_bf16_f32 v100, v182, v183
	v_cvt_pk_bf16_f32 v101, v184, v185
	v_cvt_pk_bf16_f32 v102, v124, v125
	v_cvt_pk_bf16_f32 v103, v126, v127
	v_pk_add_f32 v[118:119], v[126:127], v[106:107]
	v_pk_add_f32 v[116:117], v[124:125], v[104:105]
	s_waitcnt lgkmcnt(0)
	v_mfma_f32_32x32x16_bf16 v[128:143], v[176:179], v[172:175], v[128:143]
	v_exp_f32_e32 v120, v108
	v_exp_f32_e32 v121, v109
	v_exp_f32_e32 v122, v110
	v_exp_f32_e32 v123, v111
	v_pk_add_f32 v[110:111], v[188:189], v[118:119]
	v_pk_add_f32 v[108:109], v[186:187], v[116:117]
	v_cvt_pk_bf16_f32 v104, v186, v187
	v_cvt_pk_bf16_f32 v105, v188, v189
	v_cvt_pk_bf16_f32 v106, v120, v121
	v_cvt_pk_bf16_f32 v107, v122, v123
	v_pk_add_f32 v[178:179], v[122:123], v[110:111]
	v_pk_add_f32 v[176:177], v[120:121], v[108:109]
	s_waitcnt vmcnt(4) lgkmcnt(0)
	s_barrier
	s_add_u32 s70, s98, 0x18000
	s_addc_u32 s71, s99, 0
	s_add_i32 s68, s68, s57
	s_mov_b32 m0, s68
	s_nop 0
	global_load_lds_dwordx4 v198, s[70:71]
	s_add_i32 m0, s68, 0x400
	s_nop 0
	global_load_lds_dwordx4 v194, s[70:71]
	s_add_u32 s2, s100, 0x80
	s_addc_u32 s3, s101, 0
	s_add_i32 s49, s58, s49
	s_add_i32 m0, s49, 0xc000
	s_nop 0
	global_load_lds_dwordx4 v196, s[2:3]
	s_add_i32 m0, s49, 0xc400
	s_nop 0
	global_load_lds_dwordx4 v192, s[2:3]
	s_add_i32 s2, s46, 0xffff4000
	s_add_i32 s3, s48, 1
	s_cmp_lg_u32 s48, 2
	s_cselect_b32 s48, s3, 0
	s_and_b32 s2, s2, 0xc000
	s_add_i32 s2, s2, 0
	s_lshl_b32 s3, s48, 14
	v_add_u32_e32 v124, s2, v206
	ds_read_b128 v[108:111], v124 offset:49152
	ds_read_b128 v[116:119], v124 offset:53248
	ds_read_b128 v[120:123], v124 offset:57344
	ds_read_b128 v[124:127], v124 offset:61440
	s_waitcnt lgkmcnt(3)
	v_mfma_f32_32x32x16_bf16 v[80:95], v[108:111], v[112:115], v[80:95]
	v_xad_u32 v182, v206, 32, s2
	ds_read_b128 v[108:111], v182 offset:49152
	s_add_i32 s3, s3, 0
	s_waitcnt lgkmcnt(3)
	v_mfma_f32_32x32x16_bf16 v[64:79], v[116:119], v[112:115], v[64:79]
	ds_read_b128 v[116:119], v182 offset:53248
	s_waitcnt lgkmcnt(3)
	v_mfma_f32_32x32x16_bf16 v[16:31], v[120:123], v[112:115], v[16:31]
	ds_read_b128 v[120:123], v182 offset:57344
	s_waitcnt lgkmcnt(3)
	v_mfma_f32_32x32x16_bf16 v[0:15], v[124:127], v[112:115], v[0:15]
	ds_read_b128 v[112:115], v182 offset:61440
	s_waitcnt lgkmcnt(3)
	v_mfma_f32_32x32x16_bf16 v[80:95], v[108:111], v[96:99], v[80:95]
	v_xad_u32 v124, v206, 64, s2
	ds_read_b128 v[108:111], v124 offset:49152
	s_waitcnt lgkmcnt(3)
	v_mfma_f32_32x32x16_bf16 v[64:79], v[116:119], v[96:99], v[64:79]
	ds_read_b128 v[116:119], v124 offset:53248
	s_waitcnt lgkmcnt(3)
	v_mfma_f32_32x32x16_bf16 v[16:31], v[120:123], v[96:99], v[16:31]
	ds_read_b128 v[120:123], v124 offset:57344
	s_waitcnt lgkmcnt(3)
	v_mfma_f32_32x32x16_bf16 v[0:15], v[112:115], v[96:99], v[0:15]
	ds_read_b128 v[96:99], v124 offset:61440
	s_waitcnt lgkmcnt(3)
	v_mfma_f32_32x32x16_bf16 v[80:95], v[108:111], v[100:103], v[80:95]
	v_add_u32_e32 v124, s2, v209
	ds_read_b128 v[108:111], v124 offset:49152
	s_waitcnt lgkmcnt(3)
	v_mfma_f32_32x32x16_bf16 v[64:79], v[116:119], v[100:103], v[64:79]
	ds_read_b128 v[112:115], v124 offset:53248
	s_waitcnt lgkmcnt(3)
	v_mfma_f32_32x32x16_bf16 v[16:31], v[120:123], v[100:103], v[16:31]
	ds_read_b128 v[116:119], v124 offset:57344
	s_waitcnt lgkmcnt(3)
	v_mfma_f32_32x32x16_bf16 v[0:15], v[96:99], v[100:103], v[0:15]
	ds_read_b128 v[120:123], v124 offset:61440
	s_waitcnt lgkmcnt(3)
	v_mfma_f32_32x32x16_bf16 v[80:95], v[108:111], v[104:107], v[80:95]
	ds_read_b128 v[96:99], v205 offset:16384
	s_waitcnt lgkmcnt(3)
	v_mfma_f32_32x32x16_bf16 v[64:79], v[112:115], v[104:107], v[64:79]
	ds_read_b128 v[100:103], v205 offset:24576
	s_waitcnt lgkmcnt(3)
	v_mfma_f32_32x32x16_bf16 v[16:31], v[116:119], v[104:107], v[16:31]
	ds_read_b128 v[182:185], v211 offset:16384
	s_waitcnt lgkmcnt(3)
	v_mfma_f32_32x32x16_bf16 v[0:15], v[120:123], v[104:107], v[0:15]
	ds_read_b128 v[186:189], v211 offset:24576
	s_waitcnt lgkmcnt(3)
	v_mfma_f32_32x32x16_bf16 v[112:127], v[96:99], v[160:163], 0
	ds_read_b128 v[216:219], v212 offset:16384
	v_exp_f32_e32 v224, v144
	v_exp_f32_e32 v225, v145
	v_exp_f32_e32 v226, v146
	v_exp_f32_e32 v227, v147
	ds_read_b128 v[220:223], v212 offset:24576
	s_waitcnt lgkmcnt(4)
	v_mfma_f32_32x32x16_bf16 v[96:111], v[100:103], v[160:163], 0
	v_exp_f32_e32 v228, v148
	v_exp_f32_e32 v229, v149
	v_exp_f32_e32 v230, v150
	v_exp_f32_e32 v231, v151
	s_waitcnt lgkmcnt(3)
	v_mfma_f32_32x32x16_bf16 v[112:127], v[182:185], v[164:167], v[112:127]
	ds_read_b128 v[148:151], v213 offset:16384
	v_exp_f32_e32 v232, v152
	v_exp_f32_e32 v233, v153
	v_exp_f32_e32 v234, v154
	v_exp_f32_e32 v235, v155
	v_cvt_pk_bf16_f32 v144, v224, v225
	v_cvt_pk_bf16_f32 v145, v226, v227
	v_cvt_pk_bf16_f32 v146, v228, v229
	v_cvt_pk_bf16_f32 v147, v230, v231
	v_pk_add_f32 v[154:155], v[230:231], v[226:227]
	v_pk_add_f32 v[152:153], v[228:229], v[224:225]
	s_waitcnt lgkmcnt(3)
	v_mfma_f32_32x32x16_bf16 v[96:111], v[186:189], v[164:167], v[96:111]
	ds_read_b128 v[182:185], v213 offset:24576
	v_exp_f32_e32 v156, v156
	v_exp_f32_e32 v157, v157
	v_exp_f32_e32 v158, v158
	v_exp_f32_e32 v159, v159
	s_waitcnt lgkmcnt(3)
	v_mfma_f32_32x32x16_bf16 v[112:127], v[216:219], v[168:171], v[112:127]
	v_add_f32_e64 v154, v234, v154
	v_add_f32_e64 v155, v235, v155
	v_add_f32_e64 v152, v232, v152
	v_add_f32_e64 v153, v233, v153
	v_exp_f32_e32 v186, v128
	v_exp_f32_e32 v187, v129
	v_exp_f32_e32 v188, v130
	v_exp_f32_e32 v189, v131
	v_cvt_pk_bf16_f32 v128, v232, v233
	v_cvt_pk_bf16_f32 v129, v234, v235
	v_cvt_pk_bf16_f32 v130, v156, v157
	v_cvt_pk_bf16_f32 v131, v158, v159
	v_pk_add_f32 v[154:155], v[158:159], v[154:155]
	v_pk_add_f32 v[152:153], v[156:157], v[152:153]
	s_waitcnt lgkmcnt(2)
	v_mfma_f32_32x32x16_bf16 v[96:111], v[220:223], v[168:171], v[96:111]
	v_exp_f32_e32 v156, v132
	v_exp_f32_e32 v157, v133
	v_exp_f32_e32 v158, v134
	v_exp_f32_e32 v159, v135
	s_waitcnt lgkmcnt(1)
	v_mfma_f32_32x32x16_bf16 v[112:127], v[148:151], v[172:175], v[112:127]
	v_exp_f32_e32 v216, v136
	v_exp_f32_e32 v217, v137
	v_exp_f32_e32 v218, v138
	v_exp_f32_e32 v219, v139
	v_pk_add_f32 v[138:139], v[188:189], v[154:155]
	v_pk_add_f32 v[136:137], v[186:187], v[152:153]
	v_cvt_pk_bf16_f32 v132, v186, v187
	v_cvt_pk_bf16_f32 v133, v188, v189
	v_cvt_pk_bf16_f32 v134, v156, v157
	v_cvt_pk_bf16_f32 v135, v158, v159
	v_pk_add_f32 v[150:151], v[158:159], v[138:139]
	v_pk_add_f32 v[148:149], v[156:157], v[136:137]
	s_waitcnt lgkmcnt(0)
	v_mfma_f32_32x32x16_bf16 v[96:111], v[182:185], v[172:175], v[96:111]
	v_exp_f32_e32 v152, v140
	v_exp_f32_e32 v153, v141
	v_exp_f32_e32 v154, v142
	v_exp_f32_e32 v155, v143
	v_pk_add_f32 v[142:143], v[218:219], v[150:151]
	v_pk_add_f32 v[140:141], v[216:217], v[148:149]
	v_cvt_pk_bf16_f32 v136, v216, v217
	v_cvt_pk_bf16_f32 v137, v218, v219
	v_cvt_pk_bf16_f32 v138, v152, v153
	v_cvt_pk_bf16_f32 v139, v154, v155
	v_pk_add_f32 v[142:143], v[154:155], v[142:143]
	v_pk_add_f32 v[140:141], v[152:153], v[140:141]
	s_waitcnt vmcnt(4) lgkmcnt(0)
	v_add_f32_e32 v148, v176, v177
	v_add_f32_e32 v149, v178, v179
	v_add_f32_e32 v148, v148, v149
	v_add_f32_e32 v140, v140, v141
	v_add_f32_e32 v141, v142, v143
	s_barrier
	v_add_f32_e32 v148, v180, v148
	v_add_f32_e32 v140, v140, v141
	v_add_f32_e32 v180, v148, v140
	s_add_i32 s47, s47, 2
	s_addk_i32 s41, 0x80
	s_add_i32 s46, s46, 0x8000
	s_add_u32 s98, s98, 0x30000
	s_addc_u32 s99, s99, 0
	s_add_u32 s100, s100, 0x100
	s_addc_u32 s101, s101, 0
	s_lshl_b32 s49, s48, 14
	s_add_i32 s49, s58, s49
	s_mov_b32 m0, s49
	s_nop 0
	global_load_lds_dwordx4 v198, s[98:99]
	s_add_i32 m0, s49, 0x400
	s_nop 0
	global_load_lds_dwordx4 v194, s[98:99]
	s_add_i32 s49, s46, 0xffffc000
	s_and_b32 s49, s49, 0xc000
	s_add_i32 s49, s58, s49
	s_add_i32 m0, s49, 0xc000
	s_nop 0
	global_load_lds_dwordx4 v196, s[100:101]
	s_add_i32 m0, s49, 0xc400
	s_add_i32 s44, s48, 1
	global_load_lds_dwordx4 v192, s[100:101]
	s_cmp_lg_u32 s48, 2
	s_cselect_b32 s48, s44, 0
	s_lshl_b32 s44, s48, 14
	s_and_b32 s49, s46, 0xc000
	s_add_i32 s68, s44, 0
	s_add_i32 s44, s49, 0
	v_add_u32_e32 v156, s44, v206
	ds_read_b128 v[140:143], v156 offset:49152
	ds_read_b128 v[148:151], v156 offset:53248
	ds_read_b128 v[152:155], v156 offset:57344
	ds_read_b128 v[156:159], v156 offset:61440
	s_waitcnt lgkmcnt(3)
	v_mfma_f32_32x32x16_bf16 v[80:95], v[140:143], v[144:147], v[80:95]
	v_xad_u32 v177, v206, 32, s44
	ds_read_b128 v[140:143], v177 offset:49152
	s_waitcnt lgkmcnt(3)
	v_mfma_f32_32x32x16_bf16 v[64:79], v[148:151], v[144:147], v[64:79]
	ds_read_b128 v[148:151], v177 offset:53248
	s_waitcnt lgkmcnt(3)
	v_mfma_f32_32x32x16_bf16 v[16:31], v[152:155], v[144:147], v[16:31]
	ds_read_b128 v[152:155], v177 offset:57344
	s_waitcnt lgkmcnt(3)
	v_mfma_f32_32x32x16_bf16 v[0:15], v[156:159], v[144:147], v[0:15]
	ds_read_b128 v[144:147], v177 offset:61440
	s_waitcnt lgkmcnt(3)
	v_mfma_f32_32x32x16_bf16 v[80:95], v[140:143], v[128:131], v[80:95]
	v_xad_u32 v156, v206, 64, s44
	ds_read_b128 v[140:143], v156 offset:49152
	s_waitcnt lgkmcnt(3)
	v_mfma_f32_32x32x16_bf16 v[64:79], v[148:151], v[128:131], v[64:79]
	ds_read_b128 v[148:151], v156 offset:53248
	s_waitcnt lgkmcnt(3)
	v_mfma_f32_32x32x16_bf16 v[16:31], v[152:155], v[128:131], v[16:31]
	ds_read_b128 v[152:155], v156 offset:57344
	s_waitcnt lgkmcnt(3)
	v_mfma_f32_32x32x16_bf16 v[0:15], v[144:147], v[128:131], v[0:15]
	ds_read_b128 v[128:131], v156 offset:61440
	s_waitcnt lgkmcnt(3)
	v_mfma_f32_32x32x16_bf16 v[80:95], v[140:143], v[132:135], v[80:95]
	v_add_u32_e32 v156, s44, v209
	ds_read_b128 v[140:143], v156 offset:49152
	s_waitcnt lgkmcnt(3)
	v_mfma_f32_32x32x16_bf16 v[64:79], v[148:151], v[132:135], v[64:79]
	ds_read_b128 v[144:147], v156 offset:53248
	s_waitcnt lgkmcnt(3)
	v_mfma_f32_32x32x16_bf16 v[16:31], v[152:155], v[132:135], v[16:31]
	ds_read_b128 v[148:151], v156 offset:57344
	s_waitcnt lgkmcnt(3)
	v_mfma_f32_32x32x16_bf16 v[0:15], v[128:131], v[132:135], v[0:15]
	ds_read_b128 v[128:131], v156 offset:61440
	s_waitcnt lgkmcnt(3)
	v_mfma_f32_32x32x16_bf16 v[80:95], v[140:143], v[136:139], v[80:95]
	ds_read_b128 v[132:135], v205 offset:32768
	s_waitcnt lgkmcnt(3)
	v_mfma_f32_32x32x16_bf16 v[64:79], v[144:147], v[136:139], v[64:79]
	ds_read_b128 v[140:143], v205 offset:40960
	s_waitcnt lgkmcnt(3)
	v_mfma_f32_32x32x16_bf16 v[16:31], v[148:151], v[136:139], v[16:31]
	ds_read_b128 v[176:179], v211 offset:32768
	s_waitcnt lgkmcnt(3)
	v_mfma_f32_32x32x16_bf16 v[0:15], v[128:131], v[136:139], v[0:15]
	ds_read_b128 v[182:185], v211 offset:40960
	s_waitcnt lgkmcnt(3)
	v_mfma_f32_32x32x16_bf16 v[144:159], v[132:135], v[160:163], 0
	ds_read_b128 v[186:189], v212 offset:32768
	v_exp_f32_e32 v220, v112
	v_exp_f32_e32 v221, v113
	v_exp_f32_e32 v222, v114
	v_exp_f32_e32 v223, v115
	s_waitcnt lgkmcnt(3)
	v_mfma_f32_32x32x16_bf16 v[128:143], v[140:143], v[160:163], 0
	ds_read_b128 v[216:219], v212 offset:40960
	v_exp_f32_e32 v224, v116
	v_exp_f32_e32 v225, v117
	v_exp_f32_e32 v226, v118
	v_exp_f32_e32 v227, v119
	s_waitcnt lgkmcnt(3)
	v_mfma_f32_32x32x16_bf16 v[144:159], v[176:179], v[164:167], v[144:159]
	ds_read_b128 v[116:119], v213 offset:32768
	v_exp_f32_e32 v228, v120
	v_exp_f32_e32 v229, v121
	v_exp_f32_e32 v230, v122
	v_exp_f32_e32 v231, v123
	v_cvt_pk_bf16_f32 v112, v220, v221
	v_cvt_pk_bf16_f32 v113, v222, v223
	v_cvt_pk_bf16_f32 v114, v224, v225
	v_cvt_pk_bf16_f32 v115, v226, v227
	v_pk_add_f32 v[122:123], v[226:227], v[222:223]
	v_pk_add_f32 v[120:121], v[224:225], v[220:221]
	s_waitcnt lgkmcnt(3)
	v_mfma_f32_32x32x16_bf16 v[128:143], v[182:185], v[164:167], v[128:143]
	ds_read_b128 v[176:179], v213 offset:40960
	v_exp_f32_e32 v124, v124
	v_exp_f32_e32 v125, v125
	v_exp_f32_e32 v126, v126
	v_exp_f32_e32 v127, v127
	s_waitcnt lgkmcnt(3)
	v_mfma_f32_32x32x16_bf16 v[144:159], v[186:189], v[168:171], v[144:159]
	v_add_f32_e64 v122, v230, v122
	v_add_f32_e64 v123, v231, v123
	v_add_f32_e64 v120, v228, v120
	v_add_f32_e64 v121, v229, v121
	v_exp_f32_e32 v182, v96
	v_exp_f32_e32 v183, v97
	v_exp_f32_e32 v184, v98
	v_exp_f32_e32 v185, v99
	v_cvt_pk_bf16_f32 v96, v228, v229
	v_cvt_pk_bf16_f32 v97, v230, v231
	v_cvt_pk_bf16_f32 v98, v124, v125
	v_cvt_pk_bf16_f32 v99, v126, v127
	v_pk_add_f32 v[122:123], v[126:127], v[122:123]
	v_pk_add_f32 v[120:121], v[124:125], v[120:121]
	s_waitcnt lgkmcnt(2)
	v_mfma_f32_32x32x16_bf16 v[128:143], v[216:219], v[168:171], v[128:143]
	v_exp_f32_e32 v124, v100
	v_exp_f32_e32 v125, v101
	v_exp_f32_e32 v126, v102
	v_exp_f32_e32 v127, v103
	s_waitcnt lgkmcnt(1)
	v_mfma_f32_32x32x16_bf16 v[144:159], v[116:119], v[172:175], v[144:159]
	v_exp_f32_e32 v186, v104
	v_exp_f32_e32 v187, v105
	v_exp_f32_e32 v188, v106
	v_exp_f32_e32 v189, v107
	v_pk_add_f32 v[106:107], v[184:185], v[122:123]
	v_pk_add_f32 v[104:105], v[182:183], v[120:121]
	v_cvt_pk_bf16_f32 v100, v182, v183
	v_cvt_pk_bf16_f32 v101, v184, v185
	v_cvt_pk_bf16_f32 v102, v124, v125
	v_cvt_pk_bf16_f32 v103, v126, v127
	v_pk_add_f32 v[118:119], v[126:127], v[106:107]
	v_pk_add_f32 v[116:117], v[124:125], v[104:105]
	s_waitcnt lgkmcnt(0)
	v_mfma_f32_32x32x16_bf16 v[128:143], v[176:179], v[172:175], v[128:143]
	v_exp_f32_e32 v120, v108
	v_exp_f32_e32 v121, v109
	v_exp_f32_e32 v122, v110
	v_exp_f32_e32 v123, v111
	v_pk_add_f32 v[110:111], v[188:189], v[118:119]
	v_pk_add_f32 v[108:109], v[186:187], v[116:117]
	v_cvt_pk_bf16_f32 v104, v186, v187
	v_cvt_pk_bf16_f32 v105, v188, v189
	v_cvt_pk_bf16_f32 v106, v120, v121
	v_cvt_pk_bf16_f32 v107, v122, v123
	v_pk_add_f32 v[178:179], v[122:123], v[110:111]
	v_pk_add_f32 v[176:177], v[120:121], v[108:109]
	s_waitcnt vmcnt(4) lgkmcnt(0)
	s_barrier
	s_add_u32 s70, s98, 0x18000
	s_addc_u32 s71, s99, 0
	s_add_i32 s68, s68, s57
	s_mov_b32 m0, s68
	s_nop 0
	global_load_lds_dwordx4 v198, s[70:71]
	s_add_i32 m0, s68, 0x400
	s_nop 0
	global_load_lds_dwordx4 v194, s[70:71]
	s_add_u32 s2, s100, 0x80
	s_addc_u32 s3, s101, 0
	s_add_i32 s49, s58, s49
	s_add_i32 m0, s49, 0xc000
	s_nop 0
	global_load_lds_dwordx4 v196, s[2:3]
	s_add_i32 m0, s49, 0xc400
	s_nop 0
	global_load_lds_dwordx4 v192, s[2:3]
	s_add_i32 s2, s46, 0xffff4000
	s_add_i32 s3, s48, 1
	s_cmp_lg_u32 s48, 2
	s_cselect_b32 s48, s3, 0
	s_and_b32 s2, s2, 0xc000
	s_add_i32 s2, s2, 0
	s_lshl_b32 s3, s48, 14
	v_add_u32_e32 v124, s2, v206
	ds_read_b128 v[108:111], v124 offset:49152
	ds_read_b128 v[116:119], v124 offset:53248
	ds_read_b128 v[120:123], v124 offset:57344
	ds_read_b128 v[124:127], v124 offset:61440
	s_waitcnt lgkmcnt(3)
	v_mfma_f32_32x32x16_bf16 v[80:95], v[108:111], v[112:115], v[80:95]
	v_xad_u32 v182, v206, 32, s2
	ds_read_b128 v[108:111], v182 offset:49152
	s_add_i32 s3, s3, 0
	s_waitcnt lgkmcnt(3)
	v_mfma_f32_32x32x16_bf16 v[64:79], v[116:119], v[112:115], v[64:79]
	ds_read_b128 v[116:119], v182 offset:53248
	s_waitcnt lgkmcnt(3)
	v_mfma_f32_32x32x16_bf16 v[16:31], v[120:123], v[112:115], v[16:31]
	ds_read_b128 v[120:123], v182 offset:57344
	s_waitcnt lgkmcnt(3)
	v_mfma_f32_32x32x16_bf16 v[0:15], v[124:127], v[112:115], v[0:15]
	ds_read_b128 v[112:115], v182 offset:61440
	s_waitcnt lgkmcnt(3)
	v_mfma_f32_32x32x16_bf16 v[80:95], v[108:111], v[96:99], v[80:95]
	v_xad_u32 v124, v206, 64, s2
	ds_read_b128 v[108:111], v124 offset:49152
	s_waitcnt lgkmcnt(3)
	v_mfma_f32_32x32x16_bf16 v[64:79], v[116:119], v[96:99], v[64:79]
	ds_read_b128 v[116:119], v124 offset:53248
	s_waitcnt lgkmcnt(3)
	v_mfma_f32_32x32x16_bf16 v[16:31], v[120:123], v[96:99], v[16:31]
	ds_read_b128 v[120:123], v124 offset:57344
	s_waitcnt lgkmcnt(3)
	v_mfma_f32_32x32x16_bf16 v[0:15], v[112:115], v[96:99], v[0:15]
	ds_read_b128 v[96:99], v124 offset:61440
	s_waitcnt lgkmcnt(3)
	v_mfma_f32_32x32x16_bf16 v[80:95], v[108:111], v[100:103], v[80:95]
	v_add_u32_e32 v124, s2, v209
	ds_read_b128 v[108:111], v124 offset:49152
	s_waitcnt lgkmcnt(3)
	v_mfma_f32_32x32x16_bf16 v[64:79], v[116:119], v[100:103], v[64:79]
	ds_read_b128 v[112:115], v124 offset:53248
	s_waitcnt lgkmcnt(3)
	v_mfma_f32_32x32x16_bf16 v[16:31], v[120:123], v[100:103], v[16:31]
	ds_read_b128 v[116:119], v124 offset:57344
	s_waitcnt lgkmcnt(3)
	v_mfma_f32_32x32x16_bf16 v[0:15], v[96:99], v[100:103], v[0:15]
	ds_read_b128 v[120:123], v124 offset:61440
	s_waitcnt lgkmcnt(3)
	v_mfma_f32_32x32x16_bf16 v[80:95], v[108:111], v[104:107], v[80:95]
	ds_read_b128 v[96:99], v205
	s_waitcnt lgkmcnt(3)
	v_mfma_f32_32x32x16_bf16 v[64:79], v[112:115], v[104:107], v[64:79]
	ds_read_b128 v[100:103], v205 offset:8192
	s_waitcnt lgkmcnt(3)
	v_mfma_f32_32x32x16_bf16 v[16:31], v[116:119], v[104:107], v[16:31]
	ds_read_b128 v[182:185], v211
	s_waitcnt lgkmcnt(3)
	v_mfma_f32_32x32x16_bf16 v[0:15], v[120:123], v[104:107], v[0:15]
	ds_read_b128 v[186:189], v211 offset:8192
	s_waitcnt lgkmcnt(3)
	v_mfma_f32_32x32x16_bf16 v[112:127], v[96:99], v[160:163], 0
	ds_read_b128 v[216:219], v212
	v_exp_f32_e32 v224, v144
	v_exp_f32_e32 v225, v145
	v_exp_f32_e32 v226, v146
	v_exp_f32_e32 v227, v147
	ds_read_b128 v[220:223], v212 offset:8192
	s_waitcnt lgkmcnt(4)
	v_mfma_f32_32x32x16_bf16 v[96:111], v[100:103], v[160:163], 0
	v_exp_f32_e32 v228, v148
	v_exp_f32_e32 v229, v149
	v_exp_f32_e32 v230, v150
	v_exp_f32_e32 v231, v151
	s_waitcnt lgkmcnt(3)
	v_mfma_f32_32x32x16_bf16 v[112:127], v[182:185], v[164:167], v[112:127]
	ds_read_b128 v[148:151], v213
	v_exp_f32_e32 v232, v152
	v_exp_f32_e32 v233, v153
	v_exp_f32_e32 v234, v154
	v_exp_f32_e32 v235, v155
	v_cvt_pk_bf16_f32 v144, v224, v225
	v_cvt_pk_bf16_f32 v145, v226, v227
	v_cvt_pk_bf16_f32 v146, v228, v229
	v_cvt_pk_bf16_f32 v147, v230, v231
	v_pk_add_f32 v[154:155], v[230:231], v[226:227]
	v_pk_add_f32 v[152:153], v[228:229], v[224:225]
	s_waitcnt lgkmcnt(3)
	v_mfma_f32_32x32x16_bf16 v[96:111], v[186:189], v[164:167], v[96:111]
	ds_read_b128 v[182:185], v213 offset:8192
	v_exp_f32_e32 v156, v156
	v_exp_f32_e32 v157, v157
	v_exp_f32_e32 v158, v158
	v_exp_f32_e32 v159, v159
	s_waitcnt lgkmcnt(3)
	v_mfma_f32_32x32x16_bf16 v[112:127], v[216:219], v[168:171], v[112:127]
	v_add_f32_e64 v154, v234, v154
	v_add_f32_e64 v155, v235, v155
	v_add_f32_e64 v152, v232, v152
	v_add_f32_e64 v153, v233, v153
	v_exp_f32_e32 v186, v128
	v_exp_f32_e32 v187, v129
	v_exp_f32_e32 v188, v130
	v_exp_f32_e32 v189, v131
	v_cvt_pk_bf16_f32 v128, v232, v233
	v_cvt_pk_bf16_f32 v129, v234, v235
	v_cvt_pk_bf16_f32 v130, v156, v157
	v_cvt_pk_bf16_f32 v131, v158, v159
	v_pk_add_f32 v[154:155], v[158:159], v[154:155]
	v_pk_add_f32 v[152:153], v[156:157], v[152:153]
	s_waitcnt lgkmcnt(2)
	v_mfma_f32_32x32x16_bf16 v[96:111], v[220:223], v[168:171], v[96:111]
	v_exp_f32_e32 v156, v132
	v_exp_f32_e32 v157, v133
	v_exp_f32_e32 v158, v134
	v_exp_f32_e32 v159, v135
	s_waitcnt lgkmcnt(1)
	v_mfma_f32_32x32x16_bf16 v[112:127], v[148:151], v[172:175], v[112:127]
	v_exp_f32_e32 v216, v136
	v_exp_f32_e32 v217, v137
	v_exp_f32_e32 v218, v138
	v_exp_f32_e32 v219, v139
	v_pk_add_f32 v[138:139], v[188:189], v[154:155]
	v_pk_add_f32 v[136:137], v[186:187], v[152:153]
	v_cvt_pk_bf16_f32 v132, v186, v187
	v_cvt_pk_bf16_f32 v133, v188, v189
	v_cvt_pk_bf16_f32 v134, v156, v157
	v_cvt_pk_bf16_f32 v135, v158, v159
	v_pk_add_f32 v[150:151], v[158:159], v[138:139]
	v_pk_add_f32 v[148:149], v[156:157], v[136:137]
	s_waitcnt lgkmcnt(0)
	v_mfma_f32_32x32x16_bf16 v[96:111], v[182:185], v[172:175], v[96:111]
	v_exp_f32_e32 v152, v140
	v_exp_f32_e32 v153, v141
	v_exp_f32_e32 v154, v142
	v_exp_f32_e32 v155, v143
	v_pk_add_f32 v[142:143], v[218:219], v[150:151]
	v_pk_add_f32 v[140:141], v[216:217], v[148:149]
	v_cvt_pk_bf16_f32 v136, v216, v217
	v_cvt_pk_bf16_f32 v137, v218, v219
	v_cvt_pk_bf16_f32 v138, v152, v153
	v_cvt_pk_bf16_f32 v139, v154, v155
	v_pk_add_f32 v[142:143], v[154:155], v[142:143]
	v_pk_add_f32 v[140:141], v[152:153], v[140:141]
	s_waitcnt vmcnt(4) lgkmcnt(0)
	v_add_f32_e32 v148, v176, v177
	v_add_f32_e32 v149, v178, v179
	v_add_f32_e32 v148, v148, v149
	v_add_f32_e32 v140, v140, v141
	v_add_f32_e32 v141, v142, v143
	s_barrier
	v_add_f32_e32 v148, v180, v148
	v_add_f32_e32 v140, v140, v141
	v_add_f32_e32 v180, v148, v140
	s_add_i32 s47, s47, 2
	s_addk_i32 s41, 0x80
	s_add_i32 s46, s46, 0x8000
	s_add_u32 s98, s98, 0x30000
	s_addc_u32 s99, s99, 0
	s_add_u32 s100, s100, 0x100
	s_addc_u32 s101, s101, 0
	s_cmp_lt_u32 s47, 56
	s_cbranch_scc1 .Lst1_u3
	s_cmp_lt_u32 s47, 60
	s_cbranch_scc1 .Lst1_single
